# stack + removed redundant lgkmcnt(0) at MFMA segment heads and the mid-segment setprio 0/1 pairs
# speedup vs baseline: 1.0122x; 1.0028x over previous
; #define PG8_STAGE(bufoff, gbase, voff) do { const int so_ = (int)(unsigned)((const char*)(gbase) - base_##voff); _Pragma("unroll") for (int _i = 0; _i < 2; ++_i) \
;         __builtin_amdgcn_raw_ptr_buffer_load_lds(rs_##voff, (PG8_LAS unsigned*)(lds + (bufoff) + ldsw + _i * 8192), 16, (int)(voff)[_i], so_, 0, 0); } while (0)
; #define PG8_LDA(dst, b, h) do { _Pragma("unroll") for (int m = 0; m < 4; ++m) _Pragma("unroll") for (int k = 0; k < 2; ++k) dst[m][k] = *(const PG8_LAS bf16x8*)(lds + PG8_SA(b, h) + aoff + m * 2048 + k * 1024); } while (0)
; #define PG8_LDB(dst, b, h) do { _Pragma("unroll") for (int n = 0; n < 2; ++n) _Pragma("unroll") for (int k = 0; k < 2; ++k) dst[n][k] = *(const PG8_LAS bf16x8*)(lds + PG8_SB(b, h) + boff + n * 2048 + k * 1024); } while (0)
; #define PG8_MMA(ai, bj, At, Bt) do { __builtin_amdgcn_s_setprio(1); _Pragma("unroll") for (int m = 0; m < 4; ++m) _Pragma("unroll") for (int n = 0; n < 2; ++n) _Pragma("unroll") for (int k = 0; k < 2; ++k) \
;         acc[ai][bj][m][n] = __builtin_amdgcn_mfma_f32_16x16x32_bf16(Bt[n][k], At[m][k], acc[ai][bj][m][n], 0, 0, 0); __builtin_amdgcn_s_setprio(0); } while (0)
; #define PG8_WAIT_V(n) asm volatile("s_waitcnt vmcnt(" #n ")" ::: "memory")
; #define PG8_WAIT_L(n) asm volatile("s_waitcnt lgkmcnt(" #n ")" ::: "memory")
; #define PG8_BAR __builtin_amdgcn_s_barrier()
; #define PG8_SCHED __builtin_amdgcn_sched_barrier(0)
; template <class Epi, class Sched, bool ALIGN_EPI = false, bool SP2 = false>
; __device__ __forceinline__ void gemm_phase(PG8_LAS unsigned char* lds, const Gemm g, const Sched& S, const Epi& E, int tid_in) {
;     ...
;             PG8_LDB(B0, 0, 0); PG8_LDB(B1, 0, 1); PG8_SCHED; PG8_LDA(At, 0, 0); PG8_STAGE(PG8_SA(1, 1), a1 + hstepA, voffA);
;             PG8_WAIT_V(8); PG8_WAIT_L(0); PG8_BAR; PG8_MMA(0, 0, At, B0); PG8_MMA(0, 1, At, B1); PG8_BAR; PG8_SCHED;
;             PG8_LDA(At, 0, 1); PG8_STAGE(PG8_SB(0, 0), b2, voffB); PG8_STAGE(PG8_SB(0, 1), b2 + hstepB, voffB); PG8_STAGE(PG8_SA(0, 0), a2, voffA);
;             PG8_WAIT_V(8); PG8_WAIT_L(0); PG8_BAR; PG8_MMA(1, 0, At, B0); PG8_MMA(1, 1, At, B1); PG8_BAR; PG8_SCHED;
.LBB0_312:
	v_add_u32_e32 v0, 0x10000, v237
	ds_read_b128 v[130:133], v0
	ds_read_b128 v[134:137], v0 offset:1024
	ds_read_b128 v[138:141], v0 offset:2048
	ds_read_b128 v[142:145], v0 offset:3072
	v_add_u32_e32 v0, 0x14000, v237
	ds_read_b128 v[146:149], v0
	ds_read_b128 v[150:153], v0 offset:1024
	ds_read_b128 v[154:157], v0 offset:2048
	ds_read_b128 v[158:161], v0 offset:3072
	s_add_u32 s16, s12, 0x100
	s_addc_u32 s17, s13, 0
	s_sub_i32 s12, s12, s4
	s_add_i32 s12, s12, 0x80080
	s_sub_i32 s36, s12, 0x80000
	s_cmp_eq_u32 s23, 28
	s_cselect_b32 s13, s19, s16
	s_mov_b32 m0, s69
	ds_read_b128 v[162:165], v238
	ds_read_b128 v[166:169], v238 offset:1024
	ds_read_b128 v[170:173], v238 offset:2048
	ds_read_b128 v[174:177], v238 offset:3072
	ds_read_b128 v[178:181], v238 offset:4096
	ds_read_b128 v[182:185], v238 offset:5120
	ds_read_b128 v[186:189], v238 offset:6144
	ds_read_b128 v[190:193], v238 offset:7168
	s_mov_b32 m0, s78
	s_nop 0
	buffer_load_dwordx4 v211, s[4:7], s36 offen lds
	s_mov_b32 m0, s69
	s_nop 0
	buffer_load_dwordx4 v195, s[4:7], s12 offen lds
	s_mov_b32 m0, s67
	s_nop 0
	buffer_load_dwordx4 v211, s[4:7], s12 offen lds
	s_waitcnt vmcnt(8)
	s_waitcnt lgkmcnt(0)
	s_barrier
	s_setprio 1
	v_mfma_f32_16x16x32_bf16 v[126:129], v[130:133], v[162:165], v[126:129]
	v_mfma_f32_16x16x32_bf16 v[122:125], v[138:141], v[162:165], v[122:125]
	v_mfma_f32_16x16x32_bf16 v[106:109], v[138:141], v[170:173], v[106:109]
	v_mfma_f32_16x16x32_bf16 v[110:113], v[130:133], v[170:173], v[110:113]
	v_mfma_f32_16x16x32_bf16 v[94:97], v[130:133], v[178:181], v[94:97]
	v_mfma_f32_16x16x32_bf16 v[90:93], v[138:141], v[178:181], v[90:93]
	v_mfma_f32_16x16x32_bf16 v[74:77], v[138:141], v[186:189], v[74:77]
	v_mfma_f32_16x16x32_bf16 v[78:81], v[130:133], v[186:189], v[78:81]
	v_mfma_f32_16x16x32_bf16 v[126:129], v[134:137], v[166:169], v[126:129]
	v_mfma_f32_16x16x32_bf16 v[122:125], v[142:145], v[166:169], v[122:125]
	v_mfma_f32_16x16x32_bf16 v[106:109], v[142:145], v[174:177], v[106:109]
	v_mfma_f32_16x16x32_bf16 v[110:113], v[134:137], v[174:177], v[110:113]
	v_mfma_f32_16x16x32_bf16 v[94:97], v[134:137], v[182:185], v[94:97]
	v_mfma_f32_16x16x32_bf16 v[90:93], v[142:145], v[182:185], v[90:93]
	v_mfma_f32_16x16x32_bf16 v[74:77], v[142:145], v[190:193], v[74:77]
	v_mfma_f32_16x16x32_bf16 v[78:81], v[134:137], v[190:193], v[78:81]
	v_mfma_f32_16x16x32_bf16 v[118:121], v[146:149], v[162:165], v[118:121]
	v_mfma_f32_16x16x32_bf16 v[114:117], v[154:157], v[162:165], v[114:117]
	v_mfma_f32_16x16x32_bf16 v[98:101], v[154:157], v[170:173], v[98:101]
	v_mfma_f32_16x16x32_bf16 v[102:105], v[146:149], v[170:173], v[102:105]
	v_mfma_f32_16x16x32_bf16 v[86:89], v[146:149], v[178:181], v[86:89]
	v_mfma_f32_16x16x32_bf16 v[82:85], v[154:157], v[178:181], v[82:85]
	v_mfma_f32_16x16x32_bf16 v[66:69], v[154:157], v[186:189], v[66:69]
	v_mfma_f32_16x16x32_bf16 v[70:73], v[146:149], v[186:189], v[70:73]
	v_mfma_f32_16x16x32_bf16 v[118:121], v[150:153], v[166:169], v[118:121]
	v_mfma_f32_16x16x32_bf16 v[114:117], v[158:161], v[166:169], v[114:117]
	v_mfma_f32_16x16x32_bf16 v[98:101], v[158:161], v[174:177], v[98:101]
	v_mfma_f32_16x16x32_bf16 v[102:105], v[150:153], v[174:177], v[102:105]
	v_mfma_f32_16x16x32_bf16 v[86:89], v[150:153], v[182:185], v[86:89]
	v_mfma_f32_16x16x32_bf16 v[82:85], v[158:161], v[182:185], v[82:85]
	v_mfma_f32_16x16x32_bf16 v[66:69], v[158:161], v[190:193], v[66:69]
	v_mfma_f32_16x16x32_bf16 v[70:73], v[150:153], v[190:193], v[70:73]
	s_setprio 0
	s_barrier
	s_cselect_b32 s12, s15, s20
	s_mov_b32 m0, s61
	s_mov_b32 s42, s6
	s_mov_b32 s43, s7
	s_sub_i32 s12, s12, s40
	ds_read_b128 v[162:165], v238 offset:16384
	ds_read_b128 v[166:169], v238 offset:17408
	ds_read_b128 v[170:173], v238 offset:18432
	ds_read_b128 v[174:177], v238 offset:19456
	ds_read_b128 v[178:181], v238 offset:20480
	ds_read_b128 v[182:185], v238 offset:21504
	ds_read_b128 v[186:189], v238 offset:22528
	ds_read_b128 v[190:193], v238 offset:23552
	buffer_load_dwordx4 v207, s[40:43], s12 offen lds
	s_mov_b32 m0, s62
	s_add_i32 s36, s12, 0x80000
	buffer_load_dwordx4 v224, s[40:43], s12 offen lds
	s_mov_b32 m0, s63
	s_sub_i32 s13, s13, s4
	buffer_load_dwordx4 v207, s[40:43], s36 offen lds
	s_mov_b32 m0, s71
	s_nop 0
	buffer_load_dwordx4 v224, s[40:43], s36 offen lds
	s_mov_b32 m0, s53
	s_nop 0
	buffer_load_dwordx4 v195, s[4:7], s13 offen lds
	s_waitcnt vmcnt(7)
	s_waitcnt lgkmcnt(0)
	s_barrier
	s_setprio 1
	v_mfma_f32_16x16x32_bf16 v[62:65], v[130:133], v[162:165], v[62:65]
	v_mfma_f32_16x16x32_bf16 v[58:61], v[138:141], v[162:165], v[58:61]
	v_mfma_f32_16x16x32_bf16 v[42:45], v[138:141], v[170:173], v[42:45]
	v_mfma_f32_16x16x32_bf16 v[46:49], v[130:133], v[170:173], v[46:49]
	v_mfma_f32_16x16x32_bf16 v[30:33], v[130:133], v[178:181], v[30:33]
	v_mfma_f32_16x16x32_bf16 v[26:29], v[138:141], v[178:181], v[26:29]
	v_mfma_f32_16x16x32_bf16 v[10:13], v[138:141], v[186:189], v[10:13]
	v_mfma_f32_16x16x32_bf16 v[14:17], v[130:133], v[186:189], v[14:17]
	v_mfma_f32_16x16x32_bf16 v[62:65], v[134:137], v[166:169], v[62:65]
	v_mfma_f32_16x16x32_bf16 v[58:61], v[142:145], v[166:169], v[58:61]
	v_mfma_f32_16x16x32_bf16 v[42:45], v[142:145], v[174:177], v[42:45]
	v_mfma_f32_16x16x32_bf16 v[46:49], v[134:137], v[174:177], v[46:49]
	v_mfma_f32_16x16x32_bf16 v[30:33], v[134:137], v[182:185], v[30:33]
	v_mfma_f32_16x16x32_bf16 v[26:29], v[142:145], v[182:185], v[26:29]
	v_mfma_f32_16x16x32_bf16 v[10:13], v[142:145], v[190:193], v[10:13]
	v_mfma_f32_16x16x32_bf16 v[14:17], v[134:137], v[190:193], v[14:17]
	v_mfma_f32_16x16x32_bf16 v[54:57], v[146:149], v[162:165], v[54:57]
	v_mfma_f32_16x16x32_bf16 v[50:53], v[154:157], v[162:165], v[50:53]
	v_mfma_f32_16x16x32_bf16 v[34:37], v[154:157], v[170:173], v[34:37]
	v_mfma_f32_16x16x32_bf16 v[38:41], v[146:149], v[170:173], v[38:41]
	v_mfma_f32_16x16x32_bf16 v[22:25], v[146:149], v[178:181], v[22:25]
	v_mfma_f32_16x16x32_bf16 v[18:21], v[154:157], v[178:181], v[18:21]
	v_mfma_f32_16x16x32_bf16 v[2:5], v[154:157], v[186:189], v[2:5]
	v_mfma_f32_16x16x32_bf16 v[6:9], v[146:149], v[186:189], v[6:9]
	v_mfma_f32_16x16x32_bf16 v[54:57], v[150:153], v[166:169], v[54:57]
	v_mfma_f32_16x16x32_bf16 v[50:53], v[158:161], v[166:169], v[50:53]
	v_mfma_f32_16x16x32_bf16 v[34:37], v[158:161], v[174:177], v[34:37]
	v_mfma_f32_16x16x32_bf16 v[38:41], v[150:153], v[174:177], v[38:41]
	v_mfma_f32_16x16x32_bf16 v[22:25], v[150:153], v[182:185], v[22:25]
	v_mfma_f32_16x16x32_bf16 v[18:21], v[158:161], v[182:185], v[18:21]
	v_mfma_f32_16x16x32_bf16 v[2:5], v[158:161], v[190:193], v[2:5]
	v_mfma_f32_16x16x32_bf16 v[6:9], v[150:153], v[190:193], v[6:9]
	s_setprio 0
	s_barrier
; #define PG8_STAGE(bufoff, gbase, voff) do { const int so_ = (int)(unsigned)((const char*)(gbase) - base_##voff); _Pragma("unroll") for (int _i = 0; _i < 2; ++_i) \
;         __builtin_amdgcn_raw_ptr_buffer_load_lds(rs_##voff, (PG8_LAS unsigned*)(lds + (bufoff) + ldsw + _i * 8192), 16, (int)(voff)[_i], so_, 0, 0); } while (0)
; #define PG8_LDA(dst, b, h) do { _Pragma("unroll") for (int m = 0; m < 4; ++m) _Pragma("unroll") for (int k = 0; k < 2; ++k) dst[m][k] = *(const PG8_LAS bf16x8*)(lds + PG8_SA(b, h) + aoff + m * 2048 + k * 1024); } while (0)
; #define PG8_LDB(dst, b, h) do { _Pragma("unroll") for (int n = 0; n < 2; ++n) _Pragma("unroll") for (int k = 0; k < 2; ++k) dst[n][k] = *(const PG8_LAS bf16x8*)(lds + PG8_SB(b, h) + boff + n * 2048 + k * 1024); } while (0)
; #define PG8_MMA(ai, bj, At, Bt) do { __builtin_amdgcn_s_setprio(1); _Pragma("unroll") for (int m = 0; m < 4; ++m) _Pragma("unroll") for (int n = 0; n < 2; ++n) _Pragma("unroll") for (int k = 0; k < 2; ++k) \
;         acc[ai][bj][m][n] = __builtin_amdgcn_mfma_f32_16x16x32_bf16(Bt[n][k], At[m][k], acc[ai][bj][m][n], 0, 0, 0); __builtin_amdgcn_s_setprio(0); } while (0)
; #define PG8_WAIT_V(n) asm volatile("s_waitcnt vmcnt(" #n ")" ::: "memory")
; #define PG8_WAIT_L(n) asm volatile("s_waitcnt lgkmcnt(" #n ")" ::: "memory")
; #define PG8_BAR __builtin_amdgcn_s_barrier()
; #define PG8_SCHED __builtin_amdgcn_sched_barrier(0)
; template <class Epi, class Sched, bool ALIGN_EPI = false, bool SP2 = false>
; __device__ __forceinline__ void gemm_phase(PG8_LAS unsigned char* lds, const Gemm g, const Sched& S, const Epi& E, int tid_in) {
;     ...
;             PG8_LDB(B0, 1, 0); PG8_LDB(B1, 1, 1); PG8_SCHED; PG8_LDA(At, 1, 0); PG8_STAGE(PG8_SA(0, 1), a2 + hstepA, voffA);
;             PG8_WAIT_V(8); PG8_WAIT_L(0); PG8_BAR; PG8_MMA(0, 0, At, B0); PG8_MMA(0, 1, At, B1); PG8_BAR; PG8_SCHED;
;             PG8_LDA(At, 1, 1); PG8_STAGE(PG8_SB(1, 0), b3, voffB); PG8_STAGE(PG8_SB(1, 1), b3 + hstepB, voffB); PG8_STAGE(PG8_SA(1, 0), a3, voffA);
;             PG8_WAIT_V(8); PG8_WAIT_L(0); PG8_BAR; PG8_MMA(1, 0, At, B0); PG8_MMA(1, 1, At, B1); PG8_BAR; PG8_SCHED;
	v_add_u32_e32 v0, 0x18000, v237
	ds_read_b128 v[130:133], v0
	ds_read_b128 v[134:137], v0 offset:1024
	ds_read_b128 v[138:141], v0 offset:2048
	ds_read_b128 v[142:145], v0 offset:3072
	v_add_u32_e32 v0, 0x1c000, v237
	ds_read_b128 v[146:149], v0
	ds_read_b128 v[150:153], v0 offset:1024
	ds_read_b128 v[154:157], v0 offset:2048
	ds_read_b128 v[158:161], v0 offset:3072
	s_add_i32 s36, s13, 0x80000
	s_mov_b32 m0, s73
	ds_read_b128 v[162:165], v238 offset:32768
	ds_read_b128 v[166:169], v238 offset:33792
	ds_read_b128 v[170:173], v238 offset:34816
	ds_read_b128 v[174:177], v238 offset:35840
	ds_read_b128 v[178:181], v238 offset:36864
	ds_read_b128 v[182:185], v238 offset:37888
	ds_read_b128 v[186:189], v238 offset:38912
	ds_read_b128 v[190:193], v238 offset:39936
	s_mov_b32 m0, s72
	s_nop 0
	buffer_load_dwordx4 v211, s[4:7], s13 offen lds
	s_mov_b32 m0, s73
	s_nop 0
	buffer_load_dwordx4 v195, s[4:7], s36 offen lds
	s_mov_b32 m0, s74
	s_nop 0
	buffer_load_dwordx4 v211, s[4:7], s36 offen lds
	s_waitcnt vmcnt(8)
	s_waitcnt lgkmcnt(0)
	s_barrier
	s_setprio 1
	v_mfma_f32_16x16x32_bf16 v[126:129], v[130:133], v[162:165], v[126:129]
	v_mfma_f32_16x16x32_bf16 v[122:125], v[138:141], v[162:165], v[122:125]
	v_mfma_f32_16x16x32_bf16 v[106:109], v[138:141], v[170:173], v[106:109]
	v_mfma_f32_16x16x32_bf16 v[110:113], v[130:133], v[170:173], v[110:113]
	v_mfma_f32_16x16x32_bf16 v[94:97], v[130:133], v[178:181], v[94:97]
	v_mfma_f32_16x16x32_bf16 v[90:93], v[138:141], v[178:181], v[90:93]
	v_mfma_f32_16x16x32_bf16 v[74:77], v[138:141], v[186:189], v[74:77]
	v_mfma_f32_16x16x32_bf16 v[78:81], v[130:133], v[186:189], v[78:81]
	v_mfma_f32_16x16x32_bf16 v[126:129], v[134:137], v[166:169], v[126:129]
	v_mfma_f32_16x16x32_bf16 v[122:125], v[142:145], v[166:169], v[122:125]
	v_mfma_f32_16x16x32_bf16 v[106:109], v[142:145], v[174:177], v[106:109]
	v_mfma_f32_16x16x32_bf16 v[110:113], v[134:137], v[174:177], v[110:113]
	v_mfma_f32_16x16x32_bf16 v[94:97], v[134:137], v[182:185], v[94:97]
	v_mfma_f32_16x16x32_bf16 v[90:93], v[142:145], v[182:185], v[90:93]
	v_mfma_f32_16x16x32_bf16 v[74:77], v[142:145], v[190:193], v[74:77]
	v_mfma_f32_16x16x32_bf16 v[78:81], v[134:137], v[190:193], v[78:81]
	v_mfma_f32_16x16x32_bf16 v[118:121], v[146:149], v[162:165], v[118:121]
	v_mfma_f32_16x16x32_bf16 v[114:117], v[154:157], v[162:165], v[114:117]
	v_mfma_f32_16x16x32_bf16 v[98:101], v[154:157], v[170:173], v[98:101]
	v_mfma_f32_16x16x32_bf16 v[102:105], v[146:149], v[170:173], v[102:105]
	v_mfma_f32_16x16x32_bf16 v[86:89], v[146:149], v[178:181], v[86:89]
	v_mfma_f32_16x16x32_bf16 v[82:85], v[154:157], v[178:181], v[82:85]
	v_mfma_f32_16x16x32_bf16 v[66:69], v[154:157], v[186:189], v[66:69]
	v_mfma_f32_16x16x32_bf16 v[70:73], v[146:149], v[186:189], v[70:73]
	v_mfma_f32_16x16x32_bf16 v[118:121], v[150:153], v[166:169], v[118:121]
	v_mfma_f32_16x16x32_bf16 v[114:117], v[158:161], v[166:169], v[114:117]
	v_mfma_f32_16x16x32_bf16 v[98:101], v[158:161], v[174:177], v[98:101]
	v_mfma_f32_16x16x32_bf16 v[102:105], v[150:153], v[174:177], v[102:105]
	v_mfma_f32_16x16x32_bf16 v[86:89], v[150:153], v[182:185], v[86:89]
	v_mfma_f32_16x16x32_bf16 v[82:85], v[158:161], v[182:185], v[82:85]
	v_mfma_f32_16x16x32_bf16 v[66:69], v[158:161], v[190:193], v[66:69]
	v_mfma_f32_16x16x32_bf16 v[70:73], v[150:153], v[190:193], v[70:73]
	s_setprio 0
	s_barrier
	s_mov_b32 m0, s75
	s_add_i32 s36, s12, 0x80
	ds_read_b128 v[162:165], v238 offset:49152
	ds_read_b128 v[166:169], v238 offset:50176
	ds_read_b128 v[170:173], v238 offset:51200
	ds_read_b128 v[174:177], v238 offset:52224
	ds_read_b128 v[178:181], v238 offset:53248
	ds_read_b128 v[182:185], v238 offset:54272
	ds_read_b128 v[186:189], v238 offset:55296
	ds_read_b128 v[190:193], v238 offset:56320
	buffer_load_dwordx4 v207, s[40:43], s36 offen lds
	s_mov_b32 m0, s76
	s_add_i32 s12, s12, 0x80080
	buffer_load_dwordx4 v224, s[40:43], s36 offen lds
	s_mov_b32 m0, s79
	s_addk_i32 s13, 0x80
	buffer_load_dwordx4 v207, s[40:43], s12 offen lds
	s_mov_b32 m0, s68
	s_nop 0
	buffer_load_dwordx4 v224, s[40:43], s12 offen lds
	s_mov_b32 m0, s77
	s_nop 0
	buffer_load_dwordx4 v195, s[4:7], s13 offen lds
	s_waitcnt vmcnt(7)
	s_waitcnt lgkmcnt(0)
	s_barrier
	s_setprio 1
	v_mfma_f32_16x16x32_bf16 v[62:65], v[130:133], v[162:165], v[62:65]
	v_mfma_f32_16x16x32_bf16 v[58:61], v[138:141], v[162:165], v[58:61]
	v_mfma_f32_16x16x32_bf16 v[42:45], v[138:141], v[170:173], v[42:45]
	v_mfma_f32_16x16x32_bf16 v[46:49], v[130:133], v[170:173], v[46:49]
	v_mfma_f32_16x16x32_bf16 v[30:33], v[130:133], v[178:181], v[30:33]
	v_mfma_f32_16x16x32_bf16 v[26:29], v[138:141], v[178:181], v[26:29]
	v_mfma_f32_16x16x32_bf16 v[10:13], v[138:141], v[186:189], v[10:13]
	v_mfma_f32_16x16x32_bf16 v[14:17], v[130:133], v[186:189], v[14:17]
	v_mfma_f32_16x16x32_bf16 v[62:65], v[134:137], v[166:169], v[62:65]
	v_mfma_f32_16x16x32_bf16 v[58:61], v[142:145], v[166:169], v[58:61]
	v_mfma_f32_16x16x32_bf16 v[42:45], v[142:145], v[174:177], v[42:45]
	v_mfma_f32_16x16x32_bf16 v[46:49], v[134:137], v[174:177], v[46:49]
	v_mfma_f32_16x16x32_bf16 v[30:33], v[134:137], v[182:185], v[30:33]
	v_mfma_f32_16x16x32_bf16 v[26:29], v[142:145], v[182:185], v[26:29]
	v_mfma_f32_16x16x32_bf16 v[10:13], v[142:145], v[190:193], v[10:13]
	v_mfma_f32_16x16x32_bf16 v[14:17], v[134:137], v[190:193], v[14:17]
	v_mfma_f32_16x16x32_bf16 v[54:57], v[146:149], v[162:165], v[54:57]
	v_mfma_f32_16x16x32_bf16 v[50:53], v[154:157], v[162:165], v[50:53]
	v_mfma_f32_16x16x32_bf16 v[34:37], v[154:157], v[170:173], v[34:37]
	v_mfma_f32_16x16x32_bf16 v[38:41], v[146:149], v[170:173], v[38:41]
	v_mfma_f32_16x16x32_bf16 v[22:25], v[146:149], v[178:181], v[22:25]
	v_mfma_f32_16x16x32_bf16 v[18:21], v[154:157], v[178:181], v[18:21]
	v_mfma_f32_16x16x32_bf16 v[2:5], v[154:157], v[186:189], v[2:5]
	v_mfma_f32_16x16x32_bf16 v[6:9], v[146:149], v[186:189], v[6:9]
	v_mfma_f32_16x16x32_bf16 v[54:57], v[150:153], v[166:169], v[54:57]
	v_mfma_f32_16x16x32_bf16 v[50:53], v[158:161], v[166:169], v[50:53]
	v_mfma_f32_16x16x32_bf16 v[34:37], v[158:161], v[174:177], v[34:37]
	v_mfma_f32_16x16x32_bf16 v[38:41], v[150:153], v[174:177], v[38:41]
	v_mfma_f32_16x16x32_bf16 v[22:25], v[150:153], v[182:185], v[22:25]
	v_mfma_f32_16x16x32_bf16 v[18:21], v[158:161], v[182:185], v[18:21]
	v_mfma_f32_16x16x32_bf16 v[2:5], v[158:161], v[190:193], v[2:5]
	v_mfma_f32_16x16x32_bf16 v[6:9], v[150:153], v[190:193], v[6:9]
	s_setprio 0
	s_barrier
	s_add_i32 s23, s23, 2
	s_add_u32 s20, s20, 0x100
	s_addc_u32 s21, s21, 0
	s_cmp_gt_u32 s23, 29
	s_mov_b64 s[12:13], s[16:17]
	s_cbranch_scc0 .LBB0_312
	s_and_b64 vcc, exec, s[48:49]
	s_cbranch_vccz .LBB0_315
	s_barrier

; #define PG8_STAGE(bufoff, gbase, voff) do { const int so_ = (int)(unsigned)((const char*)(gbase) - base_##voff); _Pragma("unroll") for (int _i = 0; _i < 2; ++_i) \
;         __builtin_amdgcn_raw_ptr_buffer_load_lds(rs_##voff, (PG8_LAS unsigned*)(lds + (bufoff) + ldsw + _i * 8192), 16, (int)(voff)[_i], so_, 0, 0); } while (0)
; #define PG8_LDA(dst, b, h) do { _Pragma("unroll") for (int m = 0; m < 4; ++m) _Pragma("unroll") for (int k = 0; k < 2; ++k) dst[m][k] = *(const PG8_LAS bf16x8*)(lds + PG8_SA(b, h) + aoff + m * 2048 + k * 1024); } while (0)
; #define PG8_LDB(dst, b, h) do { _Pragma("unroll") for (int n = 0; n < 2; ++n) _Pragma("unroll") for (int k = 0; k < 2; ++k) dst[n][k] = *(const PG8_LAS bf16x8*)(lds + PG8_SB(b, h) + boff + n * 2048 + k * 1024); } while (0)
; #define PG8_MMA(ai, bj, At, Bt) do { __builtin_amdgcn_s_setprio(1); _Pragma("unroll") for (int m = 0; m < 4; ++m) _Pragma("unroll") for (int n = 0; n < 2; ++n) _Pragma("unroll") for (int k = 0; k < 2; ++k) \
;         acc[ai][bj][m][n] = __builtin_amdgcn_mfma_f32_16x16x32_bf16(Bt[n][k], At[m][k], acc[ai][bj][m][n], 0, 0, 0); __builtin_amdgcn_s_setprio(0); } while (0)
; #define PG8_WAIT_V(n) asm volatile("s_waitcnt vmcnt(" #n ")" ::: "memory")
; #define PG8_WAIT_L(n) asm volatile("s_waitcnt lgkmcnt(" #n ")" ::: "memory")
; #define PG8_BAR __builtin_amdgcn_s_barrier()
; #define PG8_SCHED __builtin_amdgcn_sched_barrier(0)
; template <class Epi, class Sched, bool ALIGN_EPI = false, bool SP2 = false>
; __device__ __forceinline__ void gemm_phase(PG8_LAS unsigned char* lds, const Gemm g, const Sched& S, const Epi& E, int tid_in) {
;     ...
;             PG8_LDB(B0, 0, 0); PG8_LDB(B1, 0, 1); PG8_SCHED; PG8_LDA(At, 0, 0); PG8_STAGE(PG8_SA(1, 1), a1 + hstepA, voffA);
;             PG8_WAIT_V(8); PG8_WAIT_L(0); PG8_BAR; PG8_MMA(0, 0, At, B0); PG8_MMA(0, 1, At, B1); PG8_BAR; PG8_SCHED;
;             PG8_LDA(At, 0, 1); PG8_STAGE(PG8_SB(0, 0), b2, voffB); PG8_STAGE(PG8_SB(0, 1), b2 + hstepB, voffB); PG8_STAGE(PG8_SA(0, 0), a2, voffA);
;             PG8_WAIT_V(8); PG8_WAIT_L(0); PG8_BAR; PG8_MMA(1, 0, At, B0); PG8_MMA(1, 1, At, B1); PG8_BAR; PG8_SCHED;
.LBB0_1037:
	v_add_u32_e32 v0, 0x10000, v236
	ds_read_b128 v[132:135], v0
	ds_read_b128 v[136:139], v0 offset:1024
	ds_read_b128 v[140:143], v0 offset:2048
	ds_read_b128 v[144:147], v0 offset:3072
	v_add_u32_e32 v0, 0x14000, v236
	ds_read_b128 v[148:151], v0
	ds_read_b128 v[152:155], v0 offset:1024
	ds_read_b128 v[156:159], v0 offset:2048
	ds_read_b128 v[160:163], v0 offset:3072
	s_add_u32 s16, s12, 0x100
	s_addc_u32 s17, s13, 0
	s_sub_i32 s12, s12, s4
	s_add_i32 s12, s12, 0xc0080
	s_sub_i32 s39, s12, 0xc0000
	s_cmp_eq_u32 s38, 12
	s_cselect_b32 s13, s24, s16
	s_mov_b32 m0, s76
	ds_read_b128 v[164:167], v237
	ds_read_b128 v[168:171], v237 offset:1024
	ds_read_b128 v[172:175], v237 offset:2048
	ds_read_b128 v[176:179], v237 offset:3072
	ds_read_b128 v[180:183], v237 offset:4096
	ds_read_b128 v[184:187], v237 offset:5120
	ds_read_b128 v[188:191], v237 offset:6144
	ds_read_b128 v[192:195], v237 offset:7168
	s_mov_b32 m0, s73
	s_nop 0
	buffer_load_dwordx4 v222, s[4:7], s39 offen lds
	s_mov_b32 m0, s76
	s_nop 0
	buffer_load_dwordx4 v220, s[4:7], s12 offen lds
	s_mov_b32 m0, s77
	s_nop 0
	buffer_load_dwordx4 v222, s[4:7], s12 offen lds
	s_waitcnt vmcnt(8)
	s_waitcnt lgkmcnt(0)
	s_barrier
	s_setprio 1
	v_mfma_f32_16x16x32_bf16 v[128:131], v[132:135], v[164:167], v[128:131]
	v_mfma_f32_16x16x32_bf16 v[124:127], v[140:143], v[164:167], v[124:127]
	v_mfma_f32_16x16x32_bf16 v[116:119], v[140:143], v[172:175], v[116:119]
	v_mfma_f32_16x16x32_bf16 v[120:123], v[132:135], v[172:175], v[120:123]
	v_mfma_f32_16x16x32_bf16 v[112:115], v[132:135], v[180:183], v[112:115]
	v_mfma_f32_16x16x32_bf16 v[108:111], v[140:143], v[180:183], v[108:111]
	v_mfma_f32_16x16x32_bf16 v[100:103], v[140:143], v[188:191], v[100:103]
	v_mfma_f32_16x16x32_bf16 v[104:107], v[132:135], v[188:191], v[104:107]
	v_mfma_f32_16x16x32_bf16 v[128:131], v[136:139], v[168:171], v[128:131]
	v_mfma_f32_16x16x32_bf16 v[124:127], v[144:147], v[168:171], v[124:127]
	v_mfma_f32_16x16x32_bf16 v[116:119], v[144:147], v[176:179], v[116:119]
	v_mfma_f32_16x16x32_bf16 v[120:123], v[136:139], v[176:179], v[120:123]
	v_mfma_f32_16x16x32_bf16 v[112:115], v[136:139], v[184:187], v[112:115]
	v_mfma_f32_16x16x32_bf16 v[108:111], v[144:147], v[184:187], v[108:111]
	v_mfma_f32_16x16x32_bf16 v[100:103], v[144:147], v[192:195], v[100:103]
	v_mfma_f32_16x16x32_bf16 v[104:107], v[136:139], v[192:195], v[104:107]
	v_mfma_f32_16x16x32_bf16 v[96:99], v[148:151], v[164:167], v[96:99]
	v_mfma_f32_16x16x32_bf16 v[92:95], v[156:159], v[164:167], v[92:95]
	v_mfma_f32_16x16x32_bf16 v[84:87], v[156:159], v[172:175], v[84:87]
	v_mfma_f32_16x16x32_bf16 v[88:91], v[148:151], v[172:175], v[88:91]
	v_mfma_f32_16x16x32_bf16 v[80:83], v[148:151], v[180:183], v[80:83]
	v_mfma_f32_16x16x32_bf16 v[76:79], v[156:159], v[180:183], v[76:79]
	v_mfma_f32_16x16x32_bf16 v[68:71], v[156:159], v[188:191], v[68:71]
	v_mfma_f32_16x16x32_bf16 v[72:75], v[148:151], v[188:191], v[72:75]
	v_mfma_f32_16x16x32_bf16 v[96:99], v[152:155], v[168:171], v[96:99]
	v_mfma_f32_16x16x32_bf16 v[92:95], v[160:163], v[168:171], v[92:95]
	v_mfma_f32_16x16x32_bf16 v[84:87], v[160:163], v[176:179], v[84:87]
	v_mfma_f32_16x16x32_bf16 v[88:91], v[152:155], v[176:179], v[88:91]
	v_mfma_f32_16x16x32_bf16 v[80:83], v[152:155], v[184:187], v[80:83]
	v_mfma_f32_16x16x32_bf16 v[76:79], v[160:163], v[184:187], v[76:79]
	v_mfma_f32_16x16x32_bf16 v[68:71], v[160:163], v[192:195], v[68:71]
	v_mfma_f32_16x16x32_bf16 v[72:75], v[152:155], v[192:195], v[72:75]
	s_setprio 0
	s_barrier
	s_cselect_b32 s12, s18, s19
	s_mov_b32 m0, s26
	s_mov_b32 s46, s6
	s_mov_b32 s47, s7
	s_sub_i32 s12, s12, s44
	ds_read_b128 v[164:167], v237 offset:16384
	ds_read_b128 v[168:171], v237 offset:17408
	ds_read_b128 v[172:175], v237 offset:18432
	ds_read_b128 v[176:179], v237 offset:19456
	ds_read_b128 v[180:183], v237 offset:20480
	ds_read_b128 v[184:187], v237 offset:21504
	ds_read_b128 v[188:191], v237 offset:22528
	ds_read_b128 v[192:195], v237 offset:23552
	buffer_load_dwordx4 v221, s[44:47], s12 offen lds
	s_mov_b32 m0, s53
	s_add_i32 s39, s12, 0x40000
	buffer_load_dwordx4 v223, s[44:47], s12 offen lds
	s_mov_b32 m0, s60
	s_sub_i32 s13, s13, s4
	buffer_load_dwordx4 v221, s[44:47], s39 offen lds
	s_mov_b32 m0, s61
	s_nop 0
	buffer_load_dwordx4 v223, s[44:47], s39 offen lds
	s_mov_b32 m0, s21
	s_nop 0
	buffer_load_dwordx4 v220, s[4:7], s13 offen lds
	s_waitcnt vmcnt(7)
	s_waitcnt lgkmcnt(0)
	s_barrier
	s_setprio 1
	v_mfma_f32_16x16x32_bf16 v[64:67], v[132:135], v[164:167], v[64:67]
	v_mfma_f32_16x16x32_bf16 v[60:63], v[140:143], v[164:167], v[60:63]
	v_mfma_f32_16x16x32_bf16 v[52:55], v[140:143], v[172:175], v[52:55]
	v_mfma_f32_16x16x32_bf16 v[56:59], v[132:135], v[172:175], v[56:59]
	v_mfma_f32_16x16x32_bf16 v[48:51], v[132:135], v[180:183], v[48:51]
	v_mfma_f32_16x16x32_bf16 v[44:47], v[140:143], v[180:183], v[44:47]
	v_mfma_f32_16x16x32_bf16 v[36:39], v[140:143], v[188:191], v[36:39]
	v_mfma_f32_16x16x32_bf16 v[40:43], v[132:135], v[188:191], v[40:43]
	v_mfma_f32_16x16x32_bf16 v[64:67], v[136:139], v[168:171], v[64:67]
	v_mfma_f32_16x16x32_bf16 v[60:63], v[144:147], v[168:171], v[60:63]
	v_mfma_f32_16x16x32_bf16 v[52:55], v[144:147], v[176:179], v[52:55]
	v_mfma_f32_16x16x32_bf16 v[56:59], v[136:139], v[176:179], v[56:59]
	v_mfma_f32_16x16x32_bf16 v[48:51], v[136:139], v[184:187], v[48:51]
	v_mfma_f32_16x16x32_bf16 v[44:47], v[144:147], v[184:187], v[44:47]
	v_mfma_f32_16x16x32_bf16 v[36:39], v[144:147], v[192:195], v[36:39]
	v_mfma_f32_16x16x32_bf16 v[40:43], v[136:139], v[192:195], v[40:43]
	v_mfma_f32_16x16x32_bf16 v[32:35], v[148:151], v[164:167], v[32:35]
	v_mfma_f32_16x16x32_bf16 v[28:31], v[156:159], v[164:167], v[28:31]
	v_mfma_f32_16x16x32_bf16 v[20:23], v[156:159], v[172:175], v[20:23]
	v_mfma_f32_16x16x32_bf16 v[24:27], v[148:151], v[172:175], v[24:27]
	v_mfma_f32_16x16x32_bf16 v[16:19], v[148:151], v[180:183], v[16:19]
	v_mfma_f32_16x16x32_bf16 v[12:15], v[156:159], v[180:183], v[12:15]
	v_mfma_f32_16x16x32_bf16 v[2:5], v[156:159], v[188:191], v[4:7]
	v_mfma_f32_16x16x32_bf16 v[8:11], v[148:151], v[188:191], v[8:11]
	v_mfma_f32_16x16x32_bf16 v[32:35], v[152:155], v[168:171], v[32:35]
	v_mfma_f32_16x16x32_bf16 v[28:31], v[160:163], v[168:171], v[28:31]
	v_mfma_f32_16x16x32_bf16 v[20:23], v[160:163], v[176:179], v[20:23]
	v_mfma_f32_16x16x32_bf16 v[24:27], v[152:155], v[176:179], v[24:27]
	v_mfma_f32_16x16x32_bf16 v[16:19], v[152:155], v[184:187], v[16:19]
	v_mfma_f32_16x16x32_bf16 v[12:15], v[160:163], v[184:187], v[12:15]
	v_mfma_f32_16x16x32_bf16 v[2:5], v[160:163], v[192:195], v[2:5]
	v_mfma_f32_16x16x32_bf16 v[8:11], v[152:155], v[192:195], v[8:11]
	s_setprio 0
	s_barrier
; #define PG8_STAGE(bufoff, gbase, voff) do { const int so_ = (int)(unsigned)((const char*)(gbase) - base_##voff); _Pragma("unroll") for (int _i = 0; _i < 2; ++_i) \
;         __builtin_amdgcn_raw_ptr_buffer_load_lds(rs_##voff, (PG8_LAS unsigned*)(lds + (bufoff) + ldsw + _i * 8192), 16, (int)(voff)[_i], so_, 0, 0); } while (0)
; #define PG8_LDA(dst, b, h) do { _Pragma("unroll") for (int m = 0; m < 4; ++m) _Pragma("unroll") for (int k = 0; k < 2; ++k) dst[m][k] = *(const PG8_LAS bf16x8*)(lds + PG8_SA(b, h) + aoff + m * 2048 + k * 1024); } while (0)
; #define PG8_LDB(dst, b, h) do { _Pragma("unroll") for (int n = 0; n < 2; ++n) _Pragma("unroll") for (int k = 0; k < 2; ++k) dst[n][k] = *(const PG8_LAS bf16x8*)(lds + PG8_SB(b, h) + boff + n * 2048 + k * 1024); } while (0)
; #define PG8_MMA(ai, bj, At, Bt) do { __builtin_amdgcn_s_setprio(1); _Pragma("unroll") for (int m = 0; m < 4; ++m) _Pragma("unroll") for (int n = 0; n < 2; ++n) _Pragma("unroll") for (int k = 0; k < 2; ++k) \
;         acc[ai][bj][m][n] = __builtin_amdgcn_mfma_f32_16x16x32_bf16(Bt[n][k], At[m][k], acc[ai][bj][m][n], 0, 0, 0); __builtin_amdgcn_s_setprio(0); } while (0)
; #define PG8_WAIT_V(n) asm volatile("s_waitcnt vmcnt(" #n ")" ::: "memory")
; #define PG8_WAIT_L(n) asm volatile("s_waitcnt lgkmcnt(" #n ")" ::: "memory")
; #define PG8_BAR __builtin_amdgcn_s_barrier()
; #define PG8_SCHED __builtin_amdgcn_sched_barrier(0)
; template <class Epi, class Sched, bool ALIGN_EPI = false, bool SP2 = false>
; __device__ __forceinline__ void gemm_phase(PG8_LAS unsigned char* lds, const Gemm g, const Sched& S, const Epi& E, int tid_in) {
;     ...
;             PG8_LDB(B0, 1, 0); PG8_LDB(B1, 1, 1); PG8_SCHED; PG8_LDA(At, 1, 0); PG8_STAGE(PG8_SA(0, 1), a2 + hstepA, voffA);
;             PG8_WAIT_V(8); PG8_WAIT_L(0); PG8_BAR; PG8_MMA(0, 0, At, B0); PG8_MMA(0, 1, At, B1); PG8_BAR; PG8_SCHED;
;             PG8_LDA(At, 1, 1); PG8_STAGE(PG8_SB(1, 0), b3, voffB); PG8_STAGE(PG8_SB(1, 1), b3 + hstepB, voffB); PG8_STAGE(PG8_SA(1, 0), a3, voffA);
;             PG8_WAIT_V(8); PG8_WAIT_L(0); PG8_BAR; PG8_MMA(1, 0, At, B0); PG8_MMA(1, 1, At, B1); PG8_BAR; PG8_SCHED;
	v_add_u32_e32 v0, 0x18000, v236
	ds_read_b128 v[132:135], v0
	ds_read_b128 v[136:139], v0 offset:1024
	ds_read_b128 v[140:143], v0 offset:2048
	ds_read_b128 v[144:147], v0 offset:3072
	v_add_u32_e32 v0, 0x1c000, v236
	ds_read_b128 v[148:151], v0
	ds_read_b128 v[152:155], v0 offset:1024
	ds_read_b128 v[156:159], v0 offset:2048
	ds_read_b128 v[160:163], v0 offset:3072
	s_add_i32 s39, s13, 0xc0000
	s_mov_b32 m0, s63
	ds_read_b128 v[164:167], v237 offset:32768
	ds_read_b128 v[168:171], v237 offset:33792
	ds_read_b128 v[172:175], v237 offset:34816
	ds_read_b128 v[176:179], v237 offset:35840
	ds_read_b128 v[180:183], v237 offset:36864
	ds_read_b128 v[184:187], v237 offset:37888
	ds_read_b128 v[188:191], v237 offset:38912
	ds_read_b128 v[192:195], v237 offset:39936
	s_mov_b32 m0, s62
	s_nop 0
	buffer_load_dwordx4 v222, s[4:7], s13 offen lds
	s_mov_b32 m0, s63
	s_nop 0
	buffer_load_dwordx4 v220, s[4:7], s39 offen lds
	s_mov_b32 m0, s66
	s_nop 0
	buffer_load_dwordx4 v222, s[4:7], s39 offen lds
	s_waitcnt vmcnt(8)
	s_waitcnt lgkmcnt(0)
	s_barrier
	s_setprio 1
	v_mfma_f32_16x16x32_bf16 v[128:131], v[132:135], v[164:167], v[128:131]
	v_mfma_f32_16x16x32_bf16 v[124:127], v[140:143], v[164:167], v[124:127]
	v_mfma_f32_16x16x32_bf16 v[116:119], v[140:143], v[172:175], v[116:119]
	v_mfma_f32_16x16x32_bf16 v[120:123], v[132:135], v[172:175], v[120:123]
	v_mfma_f32_16x16x32_bf16 v[112:115], v[132:135], v[180:183], v[112:115]
	v_mfma_f32_16x16x32_bf16 v[108:111], v[140:143], v[180:183], v[108:111]
	v_mfma_f32_16x16x32_bf16 v[100:103], v[140:143], v[188:191], v[100:103]
	v_mfma_f32_16x16x32_bf16 v[104:107], v[132:135], v[188:191], v[104:107]
	v_mfma_f32_16x16x32_bf16 v[128:131], v[136:139], v[168:171], v[128:131]
	v_mfma_f32_16x16x32_bf16 v[124:127], v[144:147], v[168:171], v[124:127]
	v_mfma_f32_16x16x32_bf16 v[116:119], v[144:147], v[176:179], v[116:119]
	v_mfma_f32_16x16x32_bf16 v[120:123], v[136:139], v[176:179], v[120:123]
	v_mfma_f32_16x16x32_bf16 v[112:115], v[136:139], v[184:187], v[112:115]
	v_mfma_f32_16x16x32_bf16 v[108:111], v[144:147], v[184:187], v[108:111]
	v_mfma_f32_16x16x32_bf16 v[100:103], v[144:147], v[192:195], v[100:103]
	v_mfma_f32_16x16x32_bf16 v[104:107], v[136:139], v[192:195], v[104:107]
	v_mfma_f32_16x16x32_bf16 v[96:99], v[148:151], v[164:167], v[96:99]
	v_mfma_f32_16x16x32_bf16 v[92:95], v[156:159], v[164:167], v[92:95]
	v_mfma_f32_16x16x32_bf16 v[84:87], v[156:159], v[172:175], v[84:87]
	v_mfma_f32_16x16x32_bf16 v[88:91], v[148:151], v[172:175], v[88:91]
	v_mfma_f32_16x16x32_bf16 v[80:83], v[148:151], v[180:183], v[80:83]
	v_mfma_f32_16x16x32_bf16 v[76:79], v[156:159], v[180:183], v[76:79]
	v_mfma_f32_16x16x32_bf16 v[68:71], v[156:159], v[188:191], v[68:71]
	v_mfma_f32_16x16x32_bf16 v[72:75], v[148:151], v[188:191], v[72:75]
	v_mfma_f32_16x16x32_bf16 v[96:99], v[152:155], v[168:171], v[96:99]
	v_mfma_f32_16x16x32_bf16 v[92:95], v[160:163], v[168:171], v[92:95]
	v_mfma_f32_16x16x32_bf16 v[84:87], v[160:163], v[176:179], v[84:87]
	v_mfma_f32_16x16x32_bf16 v[88:91], v[152:155], v[176:179], v[88:91]
	v_mfma_f32_16x16x32_bf16 v[80:83], v[152:155], v[184:187], v[80:83]
	v_mfma_f32_16x16x32_bf16 v[76:79], v[160:163], v[184:187], v[76:79]
	v_mfma_f32_16x16x32_bf16 v[68:71], v[160:163], v[192:195], v[68:71]
	v_mfma_f32_16x16x32_bf16 v[72:75], v[152:155], v[192:195], v[72:75]
	s_setprio 0
	s_barrier
	s_mov_b32 m0, s69
	s_add_i32 s39, s12, 0x80
	ds_read_b128 v[164:167], v237 offset:49152
	ds_read_b128 v[168:171], v237 offset:50176
	ds_read_b128 v[172:175], v237 offset:51200
	ds_read_b128 v[176:179], v237 offset:52224
	ds_read_b128 v[180:183], v237 offset:53248
	ds_read_b128 v[184:187], v237 offset:54272
	ds_read_b128 v[188:191], v237 offset:55296
	ds_read_b128 v[192:195], v237 offset:56320
	buffer_load_dwordx4 v221, s[44:47], s39 offen lds
	s_mov_b32 m0, s71
	s_add_i32 s12, s12, 0x40080
	buffer_load_dwordx4 v223, s[44:47], s39 offen lds
	s_mov_b32 m0, s74
	s_addk_i32 s13, 0x80
	buffer_load_dwordx4 v221, s[44:47], s12 offen lds
	s_mov_b32 m0, s75
	s_nop 0
	buffer_load_dwordx4 v223, s[44:47], s12 offen lds
	s_mov_b32 m0, s72
	s_nop 0
	buffer_load_dwordx4 v220, s[4:7], s13 offen lds
	s_waitcnt vmcnt(7)
	s_waitcnt lgkmcnt(0)
	s_barrier
	s_setprio 1
	v_mfma_f32_16x16x32_bf16 v[64:67], v[132:135], v[164:167], v[64:67]
	v_mfma_f32_16x16x32_bf16 v[60:63], v[140:143], v[164:167], v[60:63]
	v_mfma_f32_16x16x32_bf16 v[52:55], v[140:143], v[172:175], v[52:55]
	v_mfma_f32_16x16x32_bf16 v[56:59], v[132:135], v[172:175], v[56:59]
	v_mfma_f32_16x16x32_bf16 v[48:51], v[132:135], v[180:183], v[48:51]
	v_mfma_f32_16x16x32_bf16 v[44:47], v[140:143], v[180:183], v[44:47]
	v_mfma_f32_16x16x32_bf16 v[36:39], v[140:143], v[188:191], v[36:39]
	v_mfma_f32_16x16x32_bf16 v[40:43], v[132:135], v[188:191], v[40:43]
	v_mfma_f32_16x16x32_bf16 v[64:67], v[136:139], v[168:171], v[64:67]
	v_mfma_f32_16x16x32_bf16 v[60:63], v[144:147], v[168:171], v[60:63]
	v_mfma_f32_16x16x32_bf16 v[52:55], v[144:147], v[176:179], v[52:55]
	v_mfma_f32_16x16x32_bf16 v[56:59], v[136:139], v[176:179], v[56:59]
	v_mfma_f32_16x16x32_bf16 v[48:51], v[136:139], v[184:187], v[48:51]
	v_mfma_f32_16x16x32_bf16 v[44:47], v[144:147], v[184:187], v[44:47]
	v_mfma_f32_16x16x32_bf16 v[36:39], v[144:147], v[192:195], v[36:39]
	v_mfma_f32_16x16x32_bf16 v[40:43], v[136:139], v[192:195], v[40:43]
	v_mfma_f32_16x16x32_bf16 v[32:35], v[148:151], v[164:167], v[32:35]
	v_mfma_f32_16x16x32_bf16 v[28:31], v[156:159], v[164:167], v[28:31]
	v_mfma_f32_16x16x32_bf16 v[20:23], v[156:159], v[172:175], v[20:23]
	v_mfma_f32_16x16x32_bf16 v[24:27], v[148:151], v[172:175], v[24:27]
	v_mfma_f32_16x16x32_bf16 v[16:19], v[148:151], v[180:183], v[16:19]
	v_mfma_f32_16x16x32_bf16 v[12:15], v[156:159], v[180:183], v[12:15]
	v_mfma_f32_16x16x32_bf16 v[2:5], v[156:159], v[188:191], v[2:5]
	v_mfma_f32_16x16x32_bf16 v[6:9], v[148:151], v[188:191], v[8:11]
	v_mfma_f32_16x16x32_bf16 v[32:35], v[152:155], v[168:171], v[32:35]
	v_mfma_f32_16x16x32_bf16 v[28:31], v[160:163], v[168:171], v[28:31]
	v_mfma_f32_16x16x32_bf16 v[20:23], v[160:163], v[176:179], v[20:23]
	v_mfma_f32_16x16x32_bf16 v[24:27], v[152:155], v[176:179], v[24:27]
	v_mfma_f32_16x16x32_bf16 v[16:19], v[152:155], v[184:187], v[16:19]
	v_mfma_f32_16x16x32_bf16 v[12:15], v[160:163], v[184:187], v[12:15]
	v_mfma_f32_16x16x32_bf16 v[4:7], v[160:163], v[192:195], v[2:5]
	v_mfma_f32_16x16x32_bf16 v[8:11], v[152:155], v[192:195], v[6:9]
	s_setprio 0
	s_barrier
	s_add_i32 s38, s38, 2
	s_add_u32 s19, s19, 0x100
	s_addc_u32 s23, s23, 0
	s_cmp_gt_u32 s38, 13
	s_mov_b64 s[12:13], s[16:17]
	s_cbranch_scc0 .LBB0_1037
	s_and_b64 vcc, exec, s[14:15]
	s_cbranch_vccz .LBB0_1040
	s_barrier

; #define PG8_STAGE(bufoff, gbase, voff) do { const int so_ = (int)(unsigned)((const char*)(gbase) - base_##voff); _Pragma("unroll") for (int _i = 0; _i < 2; ++_i) \
;         __builtin_amdgcn_raw_ptr_buffer_load_lds(rs_##voff, (PG8_LAS unsigned*)(lds + (bufoff) + ldsw + _i * 8192), 16, (int)(voff)[_i], so_, 0, 0); } while (0)
; #define PG8_LDA(dst, b, h) do { _Pragma("unroll") for (int m = 0; m < 4; ++m) _Pragma("unroll") for (int k = 0; k < 2; ++k) dst[m][k] = *(const PG8_LAS bf16x8*)(lds + PG8_SA(b, h) + aoff + m * 2048 + k * 1024); } while (0)
; #define PG8_LDB(dst, b, h) do { _Pragma("unroll") for (int n = 0; n < 2; ++n) _Pragma("unroll") for (int k = 0; k < 2; ++k) dst[n][k] = *(const PG8_LAS bf16x8*)(lds + PG8_SB(b, h) + boff + n * 2048 + k * 1024); } while (0)
; #define PG8_MMA(ai, bj, At, Bt) do { __builtin_amdgcn_s_setprio(1); _Pragma("unroll") for (int m = 0; m < 4; ++m) _Pragma("unroll") for (int n = 0; n < 2; ++n) _Pragma("unroll") for (int k = 0; k < 2; ++k) \
;         acc[ai][bj][m][n] = __builtin_amdgcn_mfma_f32_16x16x32_bf16(Bt[n][k], At[m][k], acc[ai][bj][m][n], 0, 0, 0); __builtin_amdgcn_s_setprio(0); } while (0)
; #define PG8_WAIT_V(n) asm volatile("s_waitcnt vmcnt(" #n ")" ::: "memory")
; #define PG8_WAIT_L(n) asm volatile("s_waitcnt lgkmcnt(" #n ")" ::: "memory")
; #define PG8_BAR __builtin_amdgcn_s_barrier()
; #define PG8_SCHED __builtin_amdgcn_sched_barrier(0)
; template <class Epi, class Sched, bool ALIGN_EPI = false, bool SP2 = false>
; __device__ __forceinline__ void gemm_phase(PG8_LAS unsigned char* lds, const Gemm g, const Sched& S, const Epi& E, int tid_in) {
;     ...
;             PG8_LDB(B0, 0, 0); PG8_LDB(B1, 0, 1); PG8_SCHED; PG8_LDA(At, 0, 0); PG8_STAGE(PG8_SA(1, 1), a1 + hstepA, voffA);
;             PG8_WAIT_V(8); PG8_WAIT_L(0); PG8_BAR; PG8_MMA(0, 0, At, B0); PG8_MMA(0, 1, At, B1); PG8_BAR; PG8_SCHED;
;             PG8_LDA(At, 0, 1); PG8_STAGE(PG8_SB(0, 0), b2, voffB); PG8_STAGE(PG8_SB(0, 1), b2 + hstepB, voffB); PG8_STAGE(PG8_SA(0, 0), a2, voffA);
;             PG8_WAIT_V(8); PG8_WAIT_L(0); PG8_BAR; PG8_MMA(1, 0, At, B0); PG8_MMA(1, 1, At, B1); PG8_BAR; PG8_SCHED;
.LBB0_1265:
	v_add_u32_e32 v133, 0x10000, v131
	ds_read_b128 v[134:137], v133
	ds_read_b128 v[138:141], v133 offset:1024
	ds_read_b128 v[142:145], v133 offset:2048
	ds_read_b128 v[146:149], v133 offset:3072
	v_add_u32_e32 v133, 0x14000, v131
	ds_read_b128 v[150:153], v133
	ds_read_b128 v[154:157], v133 offset:1024
	ds_read_b128 v[158:161], v133 offset:2048
	ds_read_b128 v[166:169], v133 offset:3072
	s_add_i32 s42, s18, s44
	s_add_i32 s21, s14, s44
	s_add_i32 s79, s12, s44
	s_addk_i32 s42, 0xff80
	s_sub_i32 vcc_lo, s42, 0x80000
	s_cmp_eq_u32 s19, 28
	s_cselect_b32 s21, s15, s21
	s_mov_b32 m0, s75
	ds_read_b128 v[170:173], v132
	ds_read_b128 v[174:177], v132 offset:1024
	ds_read_b128 v[178:181], v132 offset:2048
	ds_read_b128 v[182:185], v132 offset:3072
	ds_read_b128 v[186:189], v132 offset:4096
	ds_read_b128 v[190:193], v132 offset:5120
	ds_read_b128 v[200:203], v132 offset:6144
	ds_read_b128 v[206:209], v132 offset:7168
	s_mov_b32 m0, s72
	s_nop 0
	buffer_load_dwordx4 v130, s[4:7], vcc_lo offen lds
	s_mov_b32 m0, s75
	s_nop 0
	buffer_load_dwordx4 v0, s[4:7], s42 offen lds
	s_mov_b32 m0, s76
	s_nop 0
	buffer_load_dwordx4 v130, s[4:7], s42 offen lds
	s_waitcnt vmcnt(8)
	s_waitcnt lgkmcnt(0)
	s_barrier
	s_setprio 1
	v_mfma_f32_16x16x32_bf16 v[34:37], v[134:137], v[170:173], v[34:37]
	v_mfma_f32_16x16x32_bf16 v[18:21], v[142:145], v[170:173], v[18:21]
	v_mfma_f32_16x16x32_bf16 v[78:81], v[142:145], v[178:181], v[78:81]
	v_mfma_f32_16x16x32_bf16 v[86:89], v[134:137], v[178:181], v[86:89]
	v_mfma_f32_16x16x32_bf16 v[106:109], v[134:137], v[186:189], v[106:109]
	v_mfma_f32_16x16x32_bf16 v[102:105], v[142:145], v[186:189], v[102:105]
	v_mfma_f32_16x16x32_bf16 v[122:125], v[142:145], v[200:203], v[122:125]
	v_mfma_f32_16x16x32_bf16 v[126:129], v[134:137], v[200:203], v[126:129]
	v_mfma_f32_16x16x32_bf16 v[34:37], v[138:141], v[174:177], v[34:37]
	v_mfma_f32_16x16x32_bf16 v[18:21], v[146:149], v[174:177], v[18:21]
	v_mfma_f32_16x16x32_bf16 v[78:81], v[146:149], v[182:185], v[78:81]
	v_mfma_f32_16x16x32_bf16 v[86:89], v[138:141], v[182:185], v[86:89]
	v_mfma_f32_16x16x32_bf16 v[106:109], v[138:141], v[190:193], v[106:109]
	v_mfma_f32_16x16x32_bf16 v[102:105], v[146:149], v[190:193], v[102:105]
	v_mfma_f32_16x16x32_bf16 v[122:125], v[146:149], v[206:209], v[122:125]
	v_mfma_f32_16x16x32_bf16 v[126:129], v[138:141], v[206:209], v[126:129]
	v_mfma_f32_16x16x32_bf16 v[14:17], v[150:153], v[170:173], v[14:17]
	v_mfma_f32_16x16x32_bf16 v[38:41], v[158:161], v[170:173], v[38:41]
	v_mfma_f32_16x16x32_bf16 v[90:93], v[158:161], v[178:181], v[90:93]
	v_mfma_f32_16x16x32_bf16 v[74:77], v[150:153], v[178:181], v[74:77]
	v_mfma_f32_16x16x32_bf16 v[98:101], v[150:153], v[186:189], v[98:101]
	v_mfma_f32_16x16x32_bf16 v[110:113], v[158:161], v[186:189], v[110:113]
	v_mfma_f32_16x16x32_bf16 v[114:117], v[158:161], v[200:203], v[114:117]
	v_mfma_f32_16x16x32_bf16 v[118:121], v[150:153], v[200:203], v[118:121]
	v_mfma_f32_16x16x32_bf16 v[14:17], v[154:157], v[174:177], v[14:17]
	v_mfma_f32_16x16x32_bf16 v[38:41], v[166:169], v[174:177], v[38:41]
	v_mfma_f32_16x16x32_bf16 v[90:93], v[166:169], v[182:185], v[90:93]
	v_mfma_f32_16x16x32_bf16 v[74:77], v[154:157], v[182:185], v[74:77]
	v_mfma_f32_16x16x32_bf16 v[98:101], v[154:157], v[190:193], v[98:101]
	v_mfma_f32_16x16x32_bf16 v[110:113], v[166:169], v[190:193], v[110:113]
	v_mfma_f32_16x16x32_bf16 v[114:117], v[166:169], v[206:209], v[114:117]
	v_mfma_f32_16x16x32_bf16 v[118:121], v[154:157], v[206:209], v[118:121]
	s_setprio 0
	s_barrier
	s_cselect_b32 s79, s17, s79
	s_mov_b32 m0, s49
	s_mov_b32 s42, s6
	s_mov_b32 s43, s7
	s_sub_i32 s79, s79, s40
	ds_read_b128 v[170:173], v132 offset:16384
	ds_read_b128 v[174:177], v132 offset:17408
	ds_read_b128 v[178:181], v132 offset:18432
	ds_read_b128 v[182:185], v132 offset:19456
	ds_read_b128 v[186:189], v132 offset:20480
	ds_read_b128 v[190:193], v132 offset:21504
	ds_read_b128 v[200:203], v132 offset:22528
	ds_read_b128 v[206:209], v132 offset:23552
	buffer_load_dwordx4 v0, s[40:43], s79 offen lds
	s_mov_b32 m0, s60
	s_add_i32 vcc_lo, s79, 0x80000
	buffer_load_dwordx4 v130, s[40:43], s79 offen lds
	s_mov_b32 m0, s61
	s_sub_i32 s21, s21, s4
	buffer_load_dwordx4 v0, s[40:43], vcc_lo offen lds
	s_mov_b32 m0, s62
	s_nop 0
	buffer_load_dwordx4 v130, s[40:43], vcc_lo offen lds
	s_mov_b32 m0, s35
	s_nop 0
	buffer_load_dwordx4 v0, s[4:7], s21 offen lds
	s_waitcnt vmcnt(7)
	s_waitcnt lgkmcnt(0)
	s_barrier
	s_setprio 1
	v_mfma_f32_16x16x32_bf16 v[50:53], v[134:137], v[170:173], v[50:53]
	v_mfma_f32_16x16x32_bf16 v[30:33], v[142:145], v[170:173], v[30:33]
	v_mfma_f32_16x16x32_bf16 v[58:61], v[142:145], v[178:181], v[58:61]
	v_mfma_f32_16x16x32_bf16 v[62:65], v[134:137], v[178:181], v[62:65]
	v_mfma_f32_16x16x32_bf16 v[94:97], v[134:137], v[186:189], v[94:97]
	v_mfma_f32_16x16x32_bf16 v[82:85], v[142:145], v[186:189], v[82:85]
	v_mfma_f32_16x16x32_bf16 v[26:29], v[142:145], v[200:203], v[26:29]
	v_mfma_f32_16x16x32_bf16 v[46:49], v[134:137], v[200:203], v[46:49]
	v_mfma_f32_16x16x32_bf16 v[50:53], v[138:141], v[174:177], v[50:53]
	v_mfma_f32_16x16x32_bf16 v[30:33], v[146:149], v[174:177], v[30:33]
	v_mfma_f32_16x16x32_bf16 v[58:61], v[146:149], v[182:185], v[58:61]
	v_mfma_f32_16x16x32_bf16 v[62:65], v[138:141], v[182:185], v[62:65]
	v_mfma_f32_16x16x32_bf16 v[94:97], v[138:141], v[190:193], v[94:97]
	v_mfma_f32_16x16x32_bf16 v[82:85], v[146:149], v[190:193], v[82:85]
	v_mfma_f32_16x16x32_bf16 v[26:29], v[146:149], v[206:209], v[26:29]
	v_mfma_f32_16x16x32_bf16 v[46:49], v[138:141], v[206:209], v[46:49]
	v_mfma_f32_16x16x32_bf16 v[22:25], v[150:153], v[170:173], v[22:25]
	v_mfma_f32_16x16x32_bf16 v[10:13], v[158:161], v[170:173], v[10:13]
	v_mfma_f32_16x16x32_bf16 v[66:69], v[158:161], v[178:181], v[66:69]
	v_mfma_f32_16x16x32_bf16 v[54:57], v[150:153], v[178:181], v[54:57]
	v_mfma_f32_16x16x32_bf16 v[70:73], v[150:153], v[186:189], v[70:73]
	v_mfma_f32_16x16x32_bf16 v[42:45], v[158:161], v[186:189], v[42:45]
	v_mfma_f32_16x16x32_bf16 v[2:5], v[158:161], v[200:203], v[2:5]
	v_mfma_f32_16x16x32_bf16 v[6:9], v[150:153], v[200:203], v[6:9]
	v_mfma_f32_16x16x32_bf16 v[22:25], v[154:157], v[174:177], v[22:25]
	v_mfma_f32_16x16x32_bf16 v[10:13], v[166:169], v[174:177], v[10:13]
	v_mfma_f32_16x16x32_bf16 v[66:69], v[166:169], v[182:185], v[66:69]
	v_mfma_f32_16x16x32_bf16 v[54:57], v[154:157], v[182:185], v[54:57]
	v_mfma_f32_16x16x32_bf16 v[70:73], v[154:157], v[190:193], v[70:73]
	v_mfma_f32_16x16x32_bf16 v[42:45], v[166:169], v[190:193], v[42:45]
	v_mfma_f32_16x16x32_bf16 v[2:5], v[166:169], v[206:209], v[2:5]
	v_mfma_f32_16x16x32_bf16 v[6:9], v[154:157], v[206:209], v[6:9]
	s_setprio 0
	s_barrier
; #define PG8_STAGE(bufoff, gbase, voff) do { const int so_ = (int)(unsigned)((const char*)(gbase) - base_##voff); _Pragma("unroll") for (int _i = 0; _i < 2; ++_i) \
;         __builtin_amdgcn_raw_ptr_buffer_load_lds(rs_##voff, (PG8_LAS unsigned*)(lds + (bufoff) + ldsw + _i * 8192), 16, (int)(voff)[_i], so_, 0, 0); } while (0)
; #define PG8_LDA(dst, b, h) do { _Pragma("unroll") for (int m = 0; m < 4; ++m) _Pragma("unroll") for (int k = 0; k < 2; ++k) dst[m][k] = *(const PG8_LAS bf16x8*)(lds + PG8_SA(b, h) + aoff + m * 2048 + k * 1024); } while (0)
; #define PG8_LDB(dst, b, h) do { _Pragma("unroll") for (int n = 0; n < 2; ++n) _Pragma("unroll") for (int k = 0; k < 2; ++k) dst[n][k] = *(const PG8_LAS bf16x8*)(lds + PG8_SB(b, h) + boff + n * 2048 + k * 1024); } while (0)
; #define PG8_MMA(ai, bj, At, Bt) do { __builtin_amdgcn_s_setprio(1); _Pragma("unroll") for (int m = 0; m < 4; ++m) _Pragma("unroll") for (int n = 0; n < 2; ++n) _Pragma("unroll") for (int k = 0; k < 2; ++k) \
;         acc[ai][bj][m][n] = __builtin_amdgcn_mfma_f32_16x16x32_bf16(Bt[n][k], At[m][k], acc[ai][bj][m][n], 0, 0, 0); __builtin_amdgcn_s_setprio(0); } while (0)
; #define PG8_WAIT_V(n) asm volatile("s_waitcnt vmcnt(" #n ")" ::: "memory")
; #define PG8_WAIT_L(n) asm volatile("s_waitcnt lgkmcnt(" #n ")" ::: "memory")
; #define PG8_BAR __builtin_amdgcn_s_barrier()
; #define PG8_SCHED __builtin_amdgcn_sched_barrier(0)
; template <class Epi, class Sched, bool ALIGN_EPI = false, bool SP2 = false>
; __device__ __forceinline__ void gemm_phase(PG8_LAS unsigned char* lds, const Gemm g, const Sched& S, const Epi& E, int tid_in) {
;     ...
;             PG8_LDB(B0, 1, 0); PG8_LDB(B1, 1, 1); PG8_SCHED; PG8_LDA(At, 1, 0); PG8_STAGE(PG8_SA(0, 1), a2 + hstepA, voffA);
;             PG8_WAIT_V(8); PG8_WAIT_L(0); PG8_BAR; PG8_MMA(0, 0, At, B0); PG8_MMA(0, 1, At, B1); PG8_BAR; PG8_SCHED;
;             PG8_LDA(At, 1, 1); PG8_STAGE(PG8_SB(1, 0), b3, voffB); PG8_STAGE(PG8_SB(1, 1), b3 + hstepB, voffB); PG8_STAGE(PG8_SA(1, 0), a3, voffA);
	v_add_u32_e32 v133, 0x18000, v131
	ds_read_b128 v[134:137], v133
	ds_read_b128 v[138:141], v133 offset:1024
	ds_read_b128 v[142:145], v133 offset:2048
	ds_read_b128 v[146:149], v133 offset:3072
	v_add_u32_e32 v133, 0x1c000, v131
	ds_read_b128 v[150:153], v133
	ds_read_b128 v[154:157], v133 offset:1024
	ds_read_b128 v[158:161], v133 offset:2048
	ds_read_b128 v[166:169], v133 offset:3072
	s_add_i32 vcc_lo, s21, 0x80000
	s_mov_b32 m0, s66
	ds_read_b128 v[170:173], v132 offset:32768
	ds_read_b128 v[174:177], v132 offset:33792
	ds_read_b128 v[178:181], v132 offset:34816
	ds_read_b128 v[182:185], v132 offset:35840
	ds_read_b128 v[186:189], v132 offset:36864
	ds_read_b128 v[190:193], v132 offset:37888
	ds_read_b128 v[200:203], v132 offset:38912
	ds_read_b128 v[206:209], v132 offset:39936
	s_mov_b32 m0, s63
	s_nop 0
	buffer_load_dwordx4 v130, s[4:7], s21 offen lds
	s_mov_b32 m0, s66
	s_nop 0
	buffer_load_dwordx4 v0, s[4:7], vcc_lo offen lds
	s_mov_b32 m0, s67
	s_nop 0
	buffer_load_dwordx4 v130, s[4:7], vcc_lo offen lds
	s_waitcnt vmcnt(8)
	s_waitcnt lgkmcnt(0)
	s_barrier
	s_setprio 1
	v_mfma_f32_16x16x32_bf16 v[34:37], v[134:137], v[170:173], v[34:37]
	v_mfma_f32_16x16x32_bf16 v[18:21], v[142:145], v[170:173], v[18:21]
	v_mfma_f32_16x16x32_bf16 v[78:81], v[142:145], v[178:181], v[78:81]
	v_mfma_f32_16x16x32_bf16 v[86:89], v[134:137], v[178:181], v[86:89]
	v_mfma_f32_16x16x32_bf16 v[106:109], v[134:137], v[186:189], v[106:109]
	v_mfma_f32_16x16x32_bf16 v[102:105], v[142:145], v[186:189], v[102:105]
	v_mfma_f32_16x16x32_bf16 v[122:125], v[142:145], v[200:203], v[122:125]
	v_mfma_f32_16x16x32_bf16 v[126:129], v[134:137], v[200:203], v[126:129]
	v_mfma_f32_16x16x32_bf16 v[34:37], v[138:141], v[174:177], v[34:37]
	v_mfma_f32_16x16x32_bf16 v[18:21], v[146:149], v[174:177], v[18:21]
	v_mfma_f32_16x16x32_bf16 v[78:81], v[146:149], v[182:185], v[78:81]
	v_mfma_f32_16x16x32_bf16 v[86:89], v[138:141], v[182:185], v[86:89]
	v_mfma_f32_16x16x32_bf16 v[106:109], v[138:141], v[190:193], v[106:109]
	v_mfma_f32_16x16x32_bf16 v[102:105], v[146:149], v[190:193], v[102:105]
	v_mfma_f32_16x16x32_bf16 v[122:125], v[146:149], v[206:209], v[122:125]
	v_mfma_f32_16x16x32_bf16 v[126:129], v[138:141], v[206:209], v[126:129]
	v_mfma_f32_16x16x32_bf16 v[14:17], v[150:153], v[170:173], v[14:17]
	v_mfma_f32_16x16x32_bf16 v[38:41], v[158:161], v[170:173], v[38:41]
	v_mfma_f32_16x16x32_bf16 v[90:93], v[158:161], v[178:181], v[90:93]
	v_mfma_f32_16x16x32_bf16 v[74:77], v[150:153], v[178:181], v[74:77]
	v_mfma_f32_16x16x32_bf16 v[98:101], v[150:153], v[186:189], v[98:101]
	v_mfma_f32_16x16x32_bf16 v[110:113], v[158:161], v[186:189], v[110:113]
	v_mfma_f32_16x16x32_bf16 v[114:117], v[158:161], v[200:203], v[114:117]
	v_mfma_f32_16x16x32_bf16 v[118:121], v[150:153], v[200:203], v[118:121]
	v_mfma_f32_16x16x32_bf16 v[14:17], v[154:157], v[174:177], v[14:17]
	v_mfma_f32_16x16x32_bf16 v[38:41], v[166:169], v[174:177], v[38:41]
	v_mfma_f32_16x16x32_bf16 v[90:93], v[166:169], v[182:185], v[90:93]
	v_mfma_f32_16x16x32_bf16 v[74:77], v[154:157], v[182:185], v[74:77]
	v_mfma_f32_16x16x32_bf16 v[98:101], v[154:157], v[190:193], v[98:101]
	v_mfma_f32_16x16x32_bf16 v[110:113], v[166:169], v[190:193], v[110:113]
	v_mfma_f32_16x16x32_bf16 v[114:117], v[166:169], v[206:209], v[114:117]
	v_mfma_f32_16x16x32_bf16 v[118:121], v[154:157], v[206:209], v[118:121]
	s_setprio 0
	s_barrier
	s_mov_b32 m0, s68
	s_add_i32 vcc_lo, s79, 0x80
	ds_read_b128 v[170:173], v132 offset:49152
	ds_read_b128 v[174:177], v132 offset:50176
	ds_read_b128 v[178:181], v132 offset:51200
	ds_read_b128 v[182:185], v132 offset:52224
	ds_read_b128 v[186:189], v132 offset:53248
	ds_read_b128 v[190:193], v132 offset:54272
	ds_read_b128 v[200:203], v132 offset:55296
	ds_read_b128 v[206:209], v132 offset:56320
	buffer_load_dwordx4 v0, s[40:43], vcc_lo offen lds
	s_mov_b32 m0, s69
	s_add_i32 s79, s79, 0x80080
	buffer_load_dwordx4 v130, s[40:43], vcc_lo offen lds
	s_mov_b32 m0, s73
	s_addk_i32 s21, 0x80
	buffer_load_dwordx4 v0, s[40:43], s79 offen lds
	s_mov_b32 m0, s74
	s_nop 0
	buffer_load_dwordx4 v130, s[40:43], s79 offen lds
	s_mov_b32 m0, s71
	s_nop 0
	buffer_load_dwordx4 v0, s[4:7], s21 offen lds
	s_waitcnt vmcnt(7)
	s_waitcnt lgkmcnt(0)
	s_barrier
; #define PG8_MMA(ai, bj, At, Bt) do { __builtin_amdgcn_s_setprio(1); _Pragma("unroll") for (int m = 0; m < 4; ++m) _Pragma("unroll") for (int n = 0; n < 2; ++n) _Pragma("unroll") for (int k = 0; k < 2; ++k) \
;         acc[ai][bj][m][n] = __builtin_amdgcn_mfma_f32_16x16x32_bf16(Bt[n][k], At[m][k], acc[ai][bj][m][n], 0, 0, 0); __builtin_amdgcn_s_setprio(0); } while (0)
; #define PG8_WAIT_V(n) asm volatile("s_waitcnt vmcnt(" #n ")" ::: "memory")
; #define PG8_WAIT_L(n) asm volatile("s_waitcnt lgkmcnt(" #n ")" ::: "memory")
; #define PG8_BAR __builtin_amdgcn_s_barrier()
; #define PG8_SCHED __builtin_amdgcn_sched_barrier(0)
; template <class Epi, class Sched, bool ALIGN_EPI = false, bool SP2 = false>
; __device__ __forceinline__ void gemm_phase(PG8_LAS unsigned char* lds, const Gemm g, const Sched& S, const Epi& E, int tid_in) {
;     ...
;             PG8_WAIT_V(8); PG8_WAIT_L(0); PG8_BAR; PG8_MMA(1, 0, At, B0); PG8_MMA(1, 1, At, B1); PG8_BAR; PG8_SCHED;
;     ...
;         if (zero_acc) {
; #pragma unroll
;         for (int a = 0; a < 2; ++a)
; #pragma unroll
;             for (int b = 0; b < 2; ++b)
; #pragma unroll
;                 for (int m = 0; m < 4; ++m)
; #pragma unroll
;                     for (int n = 0; n < 2; ++n) acc[a][b][m][n] = (f32x4){0.f, 0.f, 0.f, 0.f};
;         }
;         cur = nxt; cA = nA; cB = nB; ++ui;
	s_setprio 1
	v_mfma_f32_16x16x32_bf16 v[50:53], v[134:137], v[170:173], v[50:53]
	v_mfma_f32_16x16x32_bf16 v[30:33], v[142:145], v[170:173], v[30:33]
	v_mfma_f32_16x16x32_bf16 v[58:61], v[142:145], v[178:181], v[58:61]
	v_mfma_f32_16x16x32_bf16 v[62:65], v[134:137], v[178:181], v[62:65]
	v_mfma_f32_16x16x32_bf16 v[94:97], v[134:137], v[186:189], v[94:97]
	v_mfma_f32_16x16x32_bf16 v[82:85], v[142:145], v[186:189], v[82:85]
	v_mfma_f32_16x16x32_bf16 v[26:29], v[142:145], v[200:203], v[26:29]
	v_mfma_f32_16x16x32_bf16 v[46:49], v[134:137], v[200:203], v[46:49]
	v_mfma_f32_16x16x32_bf16 v[50:53], v[138:141], v[174:177], v[50:53]
	v_mfma_f32_16x16x32_bf16 v[30:33], v[146:149], v[174:177], v[30:33]
	v_mfma_f32_16x16x32_bf16 v[58:61], v[146:149], v[182:185], v[58:61]
	v_mfma_f32_16x16x32_bf16 v[62:65], v[138:141], v[182:185], v[62:65]
	v_mfma_f32_16x16x32_bf16 v[94:97], v[138:141], v[190:193], v[94:97]
	v_mfma_f32_16x16x32_bf16 v[82:85], v[146:149], v[190:193], v[82:85]
	v_mfma_f32_16x16x32_bf16 v[26:29], v[146:149], v[206:209], v[26:29]
	v_mfma_f32_16x16x32_bf16 v[46:49], v[138:141], v[206:209], v[46:49]
	v_mfma_f32_16x16x32_bf16 v[22:25], v[150:153], v[170:173], v[22:25]
	v_mfma_f32_16x16x32_bf16 v[10:13], v[158:161], v[170:173], v[10:13]
	v_mfma_f32_16x16x32_bf16 v[66:69], v[158:161], v[178:181], v[66:69]
	v_mfma_f32_16x16x32_bf16 v[54:57], v[150:153], v[178:181], v[54:57]
	v_mfma_f32_16x16x32_bf16 v[70:73], v[150:153], v[186:189], v[70:73]
	v_mfma_f32_16x16x32_bf16 v[42:45], v[158:161], v[186:189], v[42:45]
	v_mfma_f32_16x16x32_bf16 v[2:5], v[158:161], v[200:203], v[2:5]
	v_mfma_f32_16x16x32_bf16 v[6:9], v[150:153], v[200:203], v[6:9]
	v_mfma_f32_16x16x32_bf16 v[22:25], v[154:157], v[174:177], v[22:25]
	v_mfma_f32_16x16x32_bf16 v[10:13], v[166:169], v[174:177], v[10:13]
	v_mfma_f32_16x16x32_bf16 v[66:69], v[166:169], v[182:185], v[66:69]
	v_mfma_f32_16x16x32_bf16 v[54:57], v[154:157], v[182:185], v[54:57]
	v_mfma_f32_16x16x32_bf16 v[70:73], v[154:157], v[190:193], v[70:73]
	v_mfma_f32_16x16x32_bf16 v[42:45], v[166:169], v[190:193], v[42:45]
	v_mfma_f32_16x16x32_bf16 v[2:5], v[166:169], v[206:209], v[2:5]
	v_mfma_f32_16x16x32_bf16 v[6:9], v[154:157], v[206:209], v[6:9]
	s_setprio 0
	s_barrier
	s_add_i32 s19, s19, 2
	s_add_u32 s44, s44, 0x100
	s_addc_u32 s45, s45, 0
	s_cmp_gt_u32 s19, 29
	s_cbranch_scc0 .LBB0_1265
	s_andn2_b64 vcc, exec, s[38:39]
	s_cbranch_vccnz .LBB0_1257
	v_mov_b32_e32 v2, 0
	s_mov_b64 s[12:13], s[24:25]
	s_mov_b32 s10, s16
	s_mov_b32 s48, s20
	s_mov_b64 s[14:15], s[22:23]
	s_mov_b32 s13, s78
	v_mov_b32_e32 v3, v2
	v_mov_b32_e32 v4, v2
	v_mov_b32_e32 v5, v2
	v_mov_b32_e32 v6, v2
	v_mov_b32_e32 v7, v2
	v_mov_b32_e32 v8, v2
	v_mov_b32_e32 v9, v2
	v_mov_b32_e32 v42, v2
	v_mov_b32_e32 v43, v2
	v_mov_b32_e32 v44, v2
	v_mov_b32_e32 v45, v2
	v_mov_b32_e32 v70, v2
	v_mov_b32_e32 v71, v2
	v_mov_b32_e32 v72, v2
	v_mov_b32_e32 v73, v2
	v_mov_b32_e32 v66, v2
	v_mov_b32_e32 v67, v2
	v_mov_b32_e32 v68, v2
	v_mov_b32_e32 v69, v2
	v_mov_b32_e32 v54, v2
	v_mov_b32_e32 v55, v2
	v_mov_b32_e32 v56, v2
	v_mov_b32_e32 v57, v2
	v_mov_b32_e32 v10, v2
	v_mov_b32_e32 v11, v2
	v_mov_b32_e32 v12, v2
	v_mov_b32_e32 v13, v2
	v_mov_b32_e32 v22, v2
	v_mov_b32_e32 v23, v2
	v_mov_b32_e32 v24, v2
	v_mov_b32_e32 v25, v2
	v_mov_b32_e32 v26, v2
	v_mov_b32_e32 v27, v2
	v_mov_b32_e32 v28, v2
	v_mov_b32_e32 v29, v2
	v_mov_b32_e32 v46, v2
	v_mov_b32_e32 v47, v2
	v_mov_b32_e32 v48, v2
	v_mov_b32_e32 v49, v2
	v_mov_b32_e32 v82, v2
	v_mov_b32_e32 v83, v2
	v_mov_b32_e32 v84, v2
	v_mov_b32_e32 v85, v2
	v_mov_b32_e32 v94, v2
	v_mov_b32_e32 v95, v2
	v_mov_b32_e32 v96, v2
	v_mov_b32_e32 v97, v2
	v_mov_b32_e32 v58, v2
	v_mov_b32_e32 v59, v2
	v_mov_b32_e32 v60, v2
	v_mov_b32_e32 v61, v2
	v_mov_b32_e32 v62, v2
	v_mov_b32_e32 v63, v2
	v_mov_b32_e32 v64, v2
	v_mov_b32_e32 v65, v2
	v_mov_b32_e32 v30, v2
	v_mov_b32_e32 v31, v2
	v_mov_b32_e32 v32, v2
	v_mov_b32_e32 v33, v2
	v_mov_b32_e32 v50, v2
	v_mov_b32_e32 v51, v2
	v_mov_b32_e32 v52, v2
	v_mov_b32_e32 v53, v2
	v_mov_b32_e32 v114, v2
	v_mov_b32_e32 v115, v2
	v_mov_b32_e32 v116, v2
	v_mov_b32_e32 v117, v2
	v_mov_b32_e32 v118, v2
	v_mov_b32_e32 v119, v2
	v_mov_b32_e32 v120, v2
	v_mov_b32_e32 v121, v2
	v_mov_b32_e32 v110, v2
	v_mov_b32_e32 v111, v2
	v_mov_b32_e32 v112, v2
	v_mov_b32_e32 v113, v2
	v_mov_b32_e32 v98, v2
	v_mov_b32_e32 v99, v2
	v_mov_b32_e32 v100, v2
	v_mov_b32_e32 v101, v2
	v_mov_b32_e32 v90, v2
	v_mov_b32_e32 v91, v2
	v_mov_b32_e32 v92, v2
	v_mov_b32_e32 v93, v2
	v_mov_b32_e32 v74, v2
	v_mov_b32_e32 v75, v2
	v_mov_b32_e32 v76, v2
	v_mov_b32_e32 v77, v2
	v_mov_b32_e32 v38, v2
	v_mov_b32_e32 v39, v2
	v_mov_b32_e32 v40, v2
	v_mov_b32_e32 v41, v2
	v_mov_b32_e32 v14, v2
	v_mov_b32_e32 v15, v2
	v_mov_b32_e32 v16, v2
	v_mov_b32_e32 v17, v2
	v_mov_b32_e32 v122, v2
	v_mov_b32_e32 v123, v2
	v_mov_b32_e32 v124, v2
	v_mov_b32_e32 v125, v2
	v_mov_b32_e32 v126, v2
	v_mov_b32_e32 v127, v2
	v_mov_b32_e32 v128, v2
	v_mov_b32_e32 v129, v2
	v_mov_b32_e32 v102, v2
	v_mov_b32_e32 v103, v2
	v_mov_b32_e32 v104, v2
	v_mov_b32_e32 v105, v2
	v_mov_b32_e32 v106, v2
	v_mov_b32_e32 v107, v2
	v_mov_b32_e32 v108, v2
	v_mov_b32_e32 v109, v2
	v_mov_b32_e32 v78, v2
	v_mov_b32_e32 v79, v2
	v_mov_b32_e32 v80, v2
	v_mov_b32_e32 v81, v2
	v_mov_b32_e32 v86, v2
	v_mov_b32_e32 v87, v2
	v_mov_b32_e32 v88, v2
	v_mov_b32_e32 v89, v2
	v_mov_b32_e32 v18, v2
	v_mov_b32_e32 v19, v2
	v_mov_b32_e32 v20, v2
	v_mov_b32_e32 v21, v2
	v_mov_b32_e32 v34, v2
	v_mov_b32_e32 v35, v2
	v_mov_b32_e32 v36, v2
	v_mov_b32_e32 v37, v2
	s_branch .LBB0_1257

; #define PG8_STAGE(bufoff, gbase, voff) do { const int so_ = (int)(unsigned)((const char*)(gbase) - base_##voff); _Pragma("unroll") for (int _i = 0; _i < 2; ++_i) \
;         __builtin_amdgcn_raw_ptr_buffer_load_lds(rs_##voff, (PG8_LAS unsigned*)(lds + (bufoff) + ldsw + _i * 8192), 16, (int)(voff)[_i], so_, 0, 0); } while (0)
; #define PG8_LDA(dst, b, h) do { _Pragma("unroll") for (int m = 0; m < 4; ++m) _Pragma("unroll") for (int k = 0; k < 2; ++k) dst[m][k] = *(const PG8_LAS bf16x8*)(lds + PG8_SA(b, h) + aoff + m * 2048 + k * 1024); } while (0)
; #define PG8_LDB(dst, b, h) do { _Pragma("unroll") for (int n = 0; n < 2; ++n) _Pragma("unroll") for (int k = 0; k < 2; ++k) dst[n][k] = *(const PG8_LAS bf16x8*)(lds + PG8_SB(b, h) + boff + n * 2048 + k * 1024); } while (0)
; #define PG8_MMA(ai, bj, At, Bt) do { __builtin_amdgcn_s_setprio(1); _Pragma("unroll") for (int m = 0; m < 4; ++m) _Pragma("unroll") for (int n = 0; n < 2; ++n) _Pragma("unroll") for (int k = 0; k < 2; ++k) \
;         acc[ai][bj][m][n] = __builtin_amdgcn_mfma_f32_16x16x32_bf16(Bt[n][k], At[m][k], acc[ai][bj][m][n], 0, 0, 0); __builtin_amdgcn_s_setprio(0); } while (0)
; #define PG8_WAIT_V(n) asm volatile("s_waitcnt vmcnt(" #n ")" ::: "memory")
; #define PG8_WAIT_L(n) asm volatile("s_waitcnt lgkmcnt(" #n ")" ::: "memory")
; #define PG8_BAR __builtin_amdgcn_s_barrier()
; #define PG8_SCHED __builtin_amdgcn_sched_barrier(0)
; template <class Epi, class Sched, bool ALIGN_EPI = false, bool SP2 = false>
; __device__ __forceinline__ void gemm_phase(PG8_LAS unsigned char* lds, const Gemm g, const Sched& S, const Epi& E, int tid_in) {
;     ...
;             PG8_LDB(B0, 0, 0); PG8_LDB(B1, 0, 1); PG8_SCHED; PG8_LDA(At, 0, 0); PG8_STAGE(PG8_SA(1, 1), a1 + hstepA, voffA);
;             PG8_WAIT_V(8); PG8_WAIT_L(0); PG8_BAR; PG8_MMA(0, 0, At, B0); PG8_MMA(0, 1, At, B1); PG8_BAR; PG8_SCHED;
;             PG8_LDA(At, 0, 1); PG8_STAGE(PG8_SB(0, 0), b2, voffB); PG8_STAGE(PG8_SB(0, 1), b2 + hstepB, voffB); PG8_STAGE(PG8_SA(0, 0), a2, voffA);
;             PG8_WAIT_V(8); PG8_WAIT_L(0); PG8_BAR; PG8_MMA(1, 0, At, B0); PG8_MMA(1, 1, At, B1); PG8_BAR; PG8_SCHED;
.LBB0_1514:
	v_add_u32_e32 v141, 0x10000, v139
	ds_read_b128 v[130:133], v141
	ds_read_b128 v[142:145], v141 offset:1024
	ds_read_b128 v[146:149], v141 offset:2048
	ds_read_b128 v[150:153], v141 offset:3072
	v_add_u32_e32 v141, 0x14000, v139
	ds_read_b128 v[154:157], v141
	ds_read_b128 v[158:161], v141 offset:1024
	ds_read_b128 v[162:165], v141 offset:2048
	ds_read_b128 v[166:169], v141 offset:3072
	s_add_u32 s38, s16, 0x100
	s_addc_u32 s39, s17, 0
	s_sub_i32 s16, s16, s4
	s_add_i32 s16, s16, 0x80080
	s_sub_i32 s74, s16, 0x80000
	s_cmp_eq_u32 s73, 28
	s_cselect_b32 s17, s18, s38
	s_mov_b32 m0, s67
	ds_read_b128 v[170:173], v140
	ds_read_b128 v[174:177], v140 offset:1024
	ds_read_b128 v[178:181], v140 offset:2048
	ds_read_b128 v[182:185], v140 offset:3072
	ds_read_b128 v[186:189], v140 offset:4096
	ds_read_b128 v[190:193], v140 offset:5120
	ds_read_b128 v[200:203], v140 offset:6144
	ds_read_b128 v[206:209], v140 offset:7168
	s_mov_b32 m0, s62
	s_nop 0
	buffer_load_dwordx4 v135, s[4:7], s74 offen lds
	s_mov_b32 m0, s67
	s_nop 0
	buffer_load_dwordx4 v0, s[4:7], s16 offen lds
	s_mov_b32 m0, s68
	s_nop 0
	buffer_load_dwordx4 v135, s[4:7], s16 offen lds
	s_waitcnt vmcnt(8)
	s_waitcnt lgkmcnt(0)
	s_barrier
	s_setprio 1
	v_mfma_f32_16x16x32_bf16 v[126:129], v[130:133], v[170:173], v[126:129]
	v_mfma_f32_16x16x32_bf16 v[122:125], v[146:149], v[170:173], v[122:125]
	v_mfma_f32_16x16x32_bf16 v[106:109], v[146:149], v[178:181], v[106:109]
	v_mfma_f32_16x16x32_bf16 v[110:113], v[130:133], v[178:181], v[110:113]
	v_mfma_f32_16x16x32_bf16 v[94:97], v[130:133], v[186:189], v[94:97]
	v_mfma_f32_16x16x32_bf16 v[90:93], v[146:149], v[186:189], v[90:93]
	v_mfma_f32_16x16x32_bf16 v[74:77], v[146:149], v[200:203], v[74:77]
	v_mfma_f32_16x16x32_bf16 v[78:81], v[130:133], v[200:203], v[78:81]
	v_mfma_f32_16x16x32_bf16 v[126:129], v[142:145], v[174:177], v[126:129]
	v_mfma_f32_16x16x32_bf16 v[122:125], v[150:153], v[174:177], v[122:125]
	v_mfma_f32_16x16x32_bf16 v[106:109], v[150:153], v[182:185], v[106:109]
	v_mfma_f32_16x16x32_bf16 v[110:113], v[142:145], v[182:185], v[110:113]
	v_mfma_f32_16x16x32_bf16 v[94:97], v[142:145], v[190:193], v[94:97]
	v_mfma_f32_16x16x32_bf16 v[90:93], v[150:153], v[190:193], v[90:93]
	v_mfma_f32_16x16x32_bf16 v[74:77], v[150:153], v[206:209], v[74:77]
	v_mfma_f32_16x16x32_bf16 v[78:81], v[142:145], v[206:209], v[78:81]
	v_mfma_f32_16x16x32_bf16 v[118:121], v[154:157], v[170:173], v[118:121]
	v_mfma_f32_16x16x32_bf16 v[114:117], v[162:165], v[170:173], v[114:117]
	v_mfma_f32_16x16x32_bf16 v[98:101], v[162:165], v[178:181], v[98:101]
	v_mfma_f32_16x16x32_bf16 v[102:105], v[154:157], v[178:181], v[102:105]
	v_mfma_f32_16x16x32_bf16 v[86:89], v[154:157], v[186:189], v[86:89]
	v_mfma_f32_16x16x32_bf16 v[82:85], v[162:165], v[186:189], v[82:85]
	v_mfma_f32_16x16x32_bf16 v[66:69], v[162:165], v[200:203], v[66:69]
	v_mfma_f32_16x16x32_bf16 v[70:73], v[154:157], v[200:203], v[70:73]
	v_mfma_f32_16x16x32_bf16 v[118:121], v[158:161], v[174:177], v[118:121]
	v_mfma_f32_16x16x32_bf16 v[114:117], v[166:169], v[174:177], v[114:117]
	v_mfma_f32_16x16x32_bf16 v[98:101], v[166:169], v[182:185], v[98:101]
	v_mfma_f32_16x16x32_bf16 v[102:105], v[158:161], v[182:185], v[102:105]
	v_mfma_f32_16x16x32_bf16 v[86:89], v[158:161], v[190:193], v[86:89]
	v_mfma_f32_16x16x32_bf16 v[82:85], v[166:169], v[190:193], v[82:85]
	v_mfma_f32_16x16x32_bf16 v[66:69], v[166:169], v[206:209], v[66:69]
	v_mfma_f32_16x16x32_bf16 v[70:73], v[158:161], v[206:209], v[70:73]
	s_setprio 0
	s_barrier
	s_cselect_b32 s16, s15, s19
	s_mov_b32 m0, s35
	s_mov_b32 s42, s6
	s_mov_b32 s43, s7
	s_sub_i32 s16, s16, s40
	ds_read_b128 v[170:173], v140 offset:16384
	ds_read_b128 v[174:177], v140 offset:17408
	ds_read_b128 v[178:181], v140 offset:18432
	ds_read_b128 v[182:185], v140 offset:19456
	ds_read_b128 v[186:189], v140 offset:20480
	ds_read_b128 v[190:193], v140 offset:21504
	ds_read_b128 v[200:203], v140 offset:22528
	ds_read_b128 v[206:209], v140 offset:23552
	buffer_load_dwordx4 v134, s[40:43], s16 offen lds
	s_mov_b32 m0, s44
	s_add_i32 s74, s16, 0x80000
	buffer_load_dwordx4 v136, s[40:43], s16 offen lds
	s_mov_b32 m0, s45
	s_sub_i32 s17, s17, s4
	buffer_load_dwordx4 v134, s[40:43], s74 offen lds
	s_mov_b32 m0, s46
	s_nop 0
	buffer_load_dwordx4 v136, s[40:43], s74 offen lds
	s_mov_b32 m0, s34
	s_nop 0
	buffer_load_dwordx4 v0, s[4:7], s17 offen lds
	s_waitcnt vmcnt(7)
	s_waitcnt lgkmcnt(0)
	s_barrier
	s_setprio 1
	v_mfma_f32_16x16x32_bf16 v[62:65], v[130:133], v[170:173], v[62:65]
	v_mfma_f32_16x16x32_bf16 v[58:61], v[146:149], v[170:173], v[58:61]
	v_mfma_f32_16x16x32_bf16 v[42:45], v[146:149], v[178:181], v[42:45]
	v_mfma_f32_16x16x32_bf16 v[46:49], v[130:133], v[178:181], v[46:49]
	v_mfma_f32_16x16x32_bf16 v[30:33], v[130:133], v[186:189], v[30:33]
	v_mfma_f32_16x16x32_bf16 v[26:29], v[146:149], v[186:189], v[26:29]
	v_mfma_f32_16x16x32_bf16 v[10:13], v[146:149], v[200:203], v[10:13]
	v_mfma_f32_16x16x32_bf16 v[14:17], v[130:133], v[200:203], v[14:17]
	v_mfma_f32_16x16x32_bf16 v[62:65], v[142:145], v[174:177], v[62:65]
	v_mfma_f32_16x16x32_bf16 v[58:61], v[150:153], v[174:177], v[58:61]
	v_mfma_f32_16x16x32_bf16 v[42:45], v[150:153], v[182:185], v[42:45]
	v_mfma_f32_16x16x32_bf16 v[46:49], v[142:145], v[182:185], v[46:49]
	v_mfma_f32_16x16x32_bf16 v[30:33], v[142:145], v[190:193], v[30:33]
	v_mfma_f32_16x16x32_bf16 v[26:29], v[150:153], v[190:193], v[26:29]
	v_mfma_f32_16x16x32_bf16 v[10:13], v[150:153], v[206:209], v[10:13]
	v_mfma_f32_16x16x32_bf16 v[14:17], v[142:145], v[206:209], v[14:17]
	v_mfma_f32_16x16x32_bf16 v[54:57], v[154:157], v[170:173], v[54:57]
	v_mfma_f32_16x16x32_bf16 v[50:53], v[162:165], v[170:173], v[50:53]
	v_mfma_f32_16x16x32_bf16 v[34:37], v[162:165], v[178:181], v[34:37]
	v_mfma_f32_16x16x32_bf16 v[38:41], v[154:157], v[178:181], v[38:41]
	v_mfma_f32_16x16x32_bf16 v[22:25], v[154:157], v[186:189], v[22:25]
	v_mfma_f32_16x16x32_bf16 v[18:21], v[162:165], v[186:189], v[18:21]
	v_mfma_f32_16x16x32_bf16 v[2:5], v[162:165], v[200:203], v[2:5]
	v_mfma_f32_16x16x32_bf16 v[6:9], v[154:157], v[200:203], v[6:9]
	v_mfma_f32_16x16x32_bf16 v[54:57], v[158:161], v[174:177], v[54:57]
	v_mfma_f32_16x16x32_bf16 v[50:53], v[166:169], v[174:177], v[50:53]
	v_mfma_f32_16x16x32_bf16 v[34:37], v[166:169], v[182:185], v[34:37]
	v_mfma_f32_16x16x32_bf16 v[38:41], v[158:161], v[182:185], v[38:41]
	v_mfma_f32_16x16x32_bf16 v[22:25], v[158:161], v[190:193], v[22:25]
	v_mfma_f32_16x16x32_bf16 v[18:21], v[166:169], v[190:193], v[18:21]
	v_mfma_f32_16x16x32_bf16 v[2:5], v[166:169], v[206:209], v[2:5]
	v_mfma_f32_16x16x32_bf16 v[6:9], v[158:161], v[206:209], v[6:9]
	s_setprio 0
	s_barrier
; #define PG8_STAGE(bufoff, gbase, voff) do { const int so_ = (int)(unsigned)((const char*)(gbase) - base_##voff); _Pragma("unroll") for (int _i = 0; _i < 2; ++_i) \
;         __builtin_amdgcn_raw_ptr_buffer_load_lds(rs_##voff, (PG8_LAS unsigned*)(lds + (bufoff) + ldsw + _i * 8192), 16, (int)(voff)[_i], so_, 0, 0); } while (0)
; #define PG8_LDA(dst, b, h) do { _Pragma("unroll") for (int m = 0; m < 4; ++m) _Pragma("unroll") for (int k = 0; k < 2; ++k) dst[m][k] = *(const PG8_LAS bf16x8*)(lds + PG8_SA(b, h) + aoff + m * 2048 + k * 1024); } while (0)
; #define PG8_LDB(dst, b, h) do { _Pragma("unroll") for (int n = 0; n < 2; ++n) _Pragma("unroll") for (int k = 0; k < 2; ++k) dst[n][k] = *(const PG8_LAS bf16x8*)(lds + PG8_SB(b, h) + boff + n * 2048 + k * 1024); } while (0)
; #define PG8_MMA(ai, bj, At, Bt) do { __builtin_amdgcn_s_setprio(1); _Pragma("unroll") for (int m = 0; m < 4; ++m) _Pragma("unroll") for (int n = 0; n < 2; ++n) _Pragma("unroll") for (int k = 0; k < 2; ++k) \
;         acc[ai][bj][m][n] = __builtin_amdgcn_mfma_f32_16x16x32_bf16(Bt[n][k], At[m][k], acc[ai][bj][m][n], 0, 0, 0); __builtin_amdgcn_s_setprio(0); } while (0)
; #define PG8_WAIT_V(n) asm volatile("s_waitcnt vmcnt(" #n ")" ::: "memory")
; #define PG8_WAIT_L(n) asm volatile("s_waitcnt lgkmcnt(" #n ")" ::: "memory")
; #define PG8_BAR __builtin_amdgcn_s_barrier()
; #define PG8_SCHED __builtin_amdgcn_sched_barrier(0)
; template <class Epi, class Sched, bool ALIGN_EPI = false, bool SP2 = false>
; __device__ __forceinline__ void gemm_phase(PG8_LAS unsigned char* lds, const Gemm g, const Sched& S, const Epi& E, int tid_in) {
;     ...
;             PG8_LDB(B0, 1, 0); PG8_LDB(B1, 1, 1); PG8_SCHED; PG8_LDA(At, 1, 0); PG8_STAGE(PG8_SA(0, 1), a2 + hstepA, voffA);
;             PG8_WAIT_V(8); PG8_WAIT_L(0); PG8_BAR; PG8_MMA(0, 0, At, B0); PG8_MMA(0, 1, At, B1); PG8_BAR; PG8_SCHED;
;             PG8_LDA(At, 1, 1); PG8_STAGE(PG8_SB(1, 0), b3, voffB); PG8_STAGE(PG8_SB(1, 1), b3 + hstepB, voffB); PG8_STAGE(PG8_SA(1, 0), a3, voffA);
;             PG8_WAIT_V(8); PG8_WAIT_L(0); PG8_BAR; PG8_MMA(1, 0, At, B0); PG8_MMA(1, 1, At, B1); PG8_BAR; PG8_SCHED;
	v_add_u32_e32 v141, 0x18000, v139
	ds_read_b128 v[130:133], v141
	ds_read_b128 v[142:145], v141 offset:1024
	ds_read_b128 v[146:149], v141 offset:2048
	ds_read_b128 v[150:153], v141 offset:3072
	v_add_u32_e32 v141, 0x1c000, v139
	ds_read_b128 v[154:157], v141
	ds_read_b128 v[158:161], v141 offset:1024
	ds_read_b128 v[162:165], v141 offset:2048
	ds_read_b128 v[166:169], v141 offset:3072
	s_add_i32 s74, s17, 0x80000
	s_mov_b32 m0, s48
	ds_read_b128 v[170:173], v140 offset:32768
	ds_read_b128 v[174:177], v140 offset:33792
	ds_read_b128 v[178:181], v140 offset:34816
	ds_read_b128 v[182:185], v140 offset:35840
	ds_read_b128 v[186:189], v140 offset:36864
	ds_read_b128 v[190:193], v140 offset:37888
	ds_read_b128 v[200:203], v140 offset:38912
	ds_read_b128 v[206:209], v140 offset:39936
	s_mov_b32 m0, s47
	s_nop 0
	buffer_load_dwordx4 v135, s[4:7], s17 offen lds
	s_mov_b32 m0, s48
	s_nop 0
	buffer_load_dwordx4 v0, s[4:7], s74 offen lds
	s_mov_b32 m0, s49
	s_nop 0
	buffer_load_dwordx4 v135, s[4:7], s74 offen lds
	s_waitcnt vmcnt(8)
	s_waitcnt lgkmcnt(0)
	s_barrier
	s_setprio 1
	v_mfma_f32_16x16x32_bf16 v[126:129], v[130:133], v[170:173], v[126:129]
	v_mfma_f32_16x16x32_bf16 v[122:125], v[146:149], v[170:173], v[122:125]
	v_mfma_f32_16x16x32_bf16 v[106:109], v[146:149], v[178:181], v[106:109]
	v_mfma_f32_16x16x32_bf16 v[110:113], v[130:133], v[178:181], v[110:113]
	v_mfma_f32_16x16x32_bf16 v[94:97], v[130:133], v[186:189], v[94:97]
	v_mfma_f32_16x16x32_bf16 v[90:93], v[146:149], v[186:189], v[90:93]
	v_mfma_f32_16x16x32_bf16 v[74:77], v[146:149], v[200:203], v[74:77]
	v_mfma_f32_16x16x32_bf16 v[78:81], v[130:133], v[200:203], v[78:81]
	v_mfma_f32_16x16x32_bf16 v[126:129], v[142:145], v[174:177], v[126:129]
	v_mfma_f32_16x16x32_bf16 v[122:125], v[150:153], v[174:177], v[122:125]
	v_mfma_f32_16x16x32_bf16 v[106:109], v[150:153], v[182:185], v[106:109]
	v_mfma_f32_16x16x32_bf16 v[110:113], v[142:145], v[182:185], v[110:113]
	v_mfma_f32_16x16x32_bf16 v[94:97], v[142:145], v[190:193], v[94:97]
	v_mfma_f32_16x16x32_bf16 v[90:93], v[150:153], v[190:193], v[90:93]
	v_mfma_f32_16x16x32_bf16 v[74:77], v[150:153], v[206:209], v[74:77]
	v_mfma_f32_16x16x32_bf16 v[78:81], v[142:145], v[206:209], v[78:81]
	v_mfma_f32_16x16x32_bf16 v[118:121], v[154:157], v[170:173], v[118:121]
	v_mfma_f32_16x16x32_bf16 v[114:117], v[162:165], v[170:173], v[114:117]
	v_mfma_f32_16x16x32_bf16 v[98:101], v[162:165], v[178:181], v[98:101]
	v_mfma_f32_16x16x32_bf16 v[102:105], v[154:157], v[178:181], v[102:105]
	v_mfma_f32_16x16x32_bf16 v[86:89], v[154:157], v[186:189], v[86:89]
	v_mfma_f32_16x16x32_bf16 v[82:85], v[162:165], v[186:189], v[82:85]
	v_mfma_f32_16x16x32_bf16 v[66:69], v[162:165], v[200:203], v[66:69]
	v_mfma_f32_16x16x32_bf16 v[70:73], v[154:157], v[200:203], v[70:73]
	v_mfma_f32_16x16x32_bf16 v[118:121], v[158:161], v[174:177], v[118:121]
	v_mfma_f32_16x16x32_bf16 v[114:117], v[166:169], v[174:177], v[114:117]
	v_mfma_f32_16x16x32_bf16 v[98:101], v[166:169], v[182:185], v[98:101]
	v_mfma_f32_16x16x32_bf16 v[102:105], v[158:161], v[182:185], v[102:105]
	v_mfma_f32_16x16x32_bf16 v[86:89], v[158:161], v[190:193], v[86:89]
	v_mfma_f32_16x16x32_bf16 v[82:85], v[166:169], v[190:193], v[82:85]
	v_mfma_f32_16x16x32_bf16 v[66:69], v[166:169], v[206:209], v[66:69]
	v_mfma_f32_16x16x32_bf16 v[70:73], v[158:161], v[206:209], v[70:73]
	s_setprio 0
	s_barrier
	s_mov_b32 m0, s53
	s_add_i32 s74, s16, 0x80
	ds_read_b128 v[170:173], v140 offset:49152
	ds_read_b128 v[174:177], v140 offset:50176
	ds_read_b128 v[178:181], v140 offset:51200
	ds_read_b128 v[182:185], v140 offset:52224
	ds_read_b128 v[186:189], v140 offset:53248
	ds_read_b128 v[190:193], v140 offset:54272
	ds_read_b128 v[200:203], v140 offset:55296
	ds_read_b128 v[206:209], v140 offset:56320
	buffer_load_dwordx4 v134, s[40:43], s74 offen lds
	s_mov_b32 m0, s60
	s_add_i32 s16, s16, 0x80080
	buffer_load_dwordx4 v136, s[40:43], s74 offen lds
	s_mov_b32 m0, s63
	s_addk_i32 s17, 0x80
	buffer_load_dwordx4 v134, s[40:43], s16 offen lds
	s_mov_b32 m0, s66
	s_nop 0
	buffer_load_dwordx4 v136, s[40:43], s16 offen lds
	s_mov_b32 m0, s61
	s_nop 0
	buffer_load_dwordx4 v0, s[4:7], s17 offen lds
	s_waitcnt vmcnt(7)
	s_waitcnt lgkmcnt(0)
	s_barrier
	s_setprio 1
	v_mfma_f32_16x16x32_bf16 v[62:65], v[130:133], v[170:173], v[62:65]
	v_mfma_f32_16x16x32_bf16 v[58:61], v[146:149], v[170:173], v[58:61]
	v_mfma_f32_16x16x32_bf16 v[42:45], v[146:149], v[178:181], v[42:45]
	v_mfma_f32_16x16x32_bf16 v[46:49], v[130:133], v[178:181], v[46:49]
	v_mfma_f32_16x16x32_bf16 v[30:33], v[130:133], v[186:189], v[30:33]
	v_mfma_f32_16x16x32_bf16 v[26:29], v[146:149], v[186:189], v[26:29]
	v_mfma_f32_16x16x32_bf16 v[10:13], v[146:149], v[200:203], v[10:13]
	v_mfma_f32_16x16x32_bf16 v[14:17], v[130:133], v[200:203], v[14:17]
	v_mfma_f32_16x16x32_bf16 v[62:65], v[142:145], v[174:177], v[62:65]
	v_mfma_f32_16x16x32_bf16 v[58:61], v[150:153], v[174:177], v[58:61]
	v_mfma_f32_16x16x32_bf16 v[42:45], v[150:153], v[182:185], v[42:45]
	v_mfma_f32_16x16x32_bf16 v[46:49], v[142:145], v[182:185], v[46:49]
	v_mfma_f32_16x16x32_bf16 v[30:33], v[142:145], v[190:193], v[30:33]
	v_mfma_f32_16x16x32_bf16 v[26:29], v[150:153], v[190:193], v[26:29]
	v_mfma_f32_16x16x32_bf16 v[10:13], v[150:153], v[206:209], v[10:13]
	v_mfma_f32_16x16x32_bf16 v[14:17], v[142:145], v[206:209], v[14:17]
	v_mfma_f32_16x16x32_bf16 v[54:57], v[154:157], v[170:173], v[54:57]
	v_mfma_f32_16x16x32_bf16 v[50:53], v[162:165], v[170:173], v[50:53]
	v_mfma_f32_16x16x32_bf16 v[34:37], v[162:165], v[178:181], v[34:37]
	v_mfma_f32_16x16x32_bf16 v[38:41], v[154:157], v[178:181], v[38:41]
	v_mfma_f32_16x16x32_bf16 v[22:25], v[154:157], v[186:189], v[22:25]
	v_mfma_f32_16x16x32_bf16 v[18:21], v[162:165], v[186:189], v[18:21]
	v_mfma_f32_16x16x32_bf16 v[2:5], v[162:165], v[200:203], v[2:5]
	v_mfma_f32_16x16x32_bf16 v[6:9], v[154:157], v[200:203], v[6:9]
	v_mfma_f32_16x16x32_bf16 v[54:57], v[158:161], v[174:177], v[54:57]
	v_mfma_f32_16x16x32_bf16 v[50:53], v[166:169], v[174:177], v[50:53]
	v_mfma_f32_16x16x32_bf16 v[34:37], v[166:169], v[182:185], v[34:37]
	v_mfma_f32_16x16x32_bf16 v[38:41], v[158:161], v[182:185], v[38:41]
	v_mfma_f32_16x16x32_bf16 v[22:25], v[158:161], v[190:193], v[22:25]
	v_mfma_f32_16x16x32_bf16 v[18:21], v[166:169], v[190:193], v[18:21]
	v_mfma_f32_16x16x32_bf16 v[2:5], v[166:169], v[206:209], v[2:5]
	v_mfma_f32_16x16x32_bf16 v[6:9], v[158:161], v[206:209], v[6:9]
	s_setprio 0
	s_barrier
	s_add_i32 s73, s73, 2
	s_add_u32 s19, s19, 0x100
	s_addc_u32 s21, s21, 0
	s_cmp_gt_u32 s73, 29
	s_mov_b64 s[16:17], s[38:39]
	s_cbranch_scc0 .LBB0_1514
	s_and_b64 vcc, exec, s[12:13]
	s_cbranch_vccz .LBB0_1517
	s_barrier

; #define PG8_STAGE(bufoff, gbase, voff) do { const int so_ = (int)(unsigned)((const char*)(gbase) - base_##voff); _Pragma("unroll") for (int _i = 0; _i < 2; ++_i) \
;         __builtin_amdgcn_raw_ptr_buffer_load_lds(rs_##voff, (PG8_LAS unsigned*)(lds + (bufoff) + ldsw + _i * 8192), 16, (int)(voff)[_i], so_, 0, 0); } while (0)
; #define PG8_LDA(dst, b, h) do { _Pragma("unroll") for (int m = 0; m < 4; ++m) _Pragma("unroll") for (int k = 0; k < 2; ++k) dst[m][k] = *(const PG8_LAS bf16x8*)(lds + PG8_SA(b, h) + aoff + m * 2048 + k * 1024); } while (0)
; #define PG8_LDB(dst, b, h) do { _Pragma("unroll") for (int n = 0; n < 2; ++n) _Pragma("unroll") for (int k = 0; k < 2; ++k) dst[n][k] = *(const PG8_LAS bf16x8*)(lds + PG8_SB(b, h) + boff + n * 2048 + k * 1024); } while (0)
; #define PG8_MMA(ai, bj, At, Bt) do { __builtin_amdgcn_s_setprio(1); _Pragma("unroll") for (int m = 0; m < 4; ++m) _Pragma("unroll") for (int n = 0; n < 2; ++n) _Pragma("unroll") for (int k = 0; k < 2; ++k) \
;         acc[ai][bj][m][n] = __builtin_amdgcn_mfma_f32_16x16x32_bf16(Bt[n][k], At[m][k], acc[ai][bj][m][n], 0, 0, 0); __builtin_amdgcn_s_setprio(0); } while (0)
; #define PG8_WAIT_V(n) asm volatile("s_waitcnt vmcnt(" #n ")" ::: "memory")
; #define PG8_WAIT_L(n) asm volatile("s_waitcnt lgkmcnt(" #n ")" ::: "memory")
; #define PG8_BAR __builtin_amdgcn_s_barrier()
; #define PG8_SCHED __builtin_amdgcn_sched_barrier(0)
; template <class Epi, class Sched, bool ALIGN_EPI = false, bool SP2 = false>
; __device__ __forceinline__ void gemm_phase(PG8_LAS unsigned char* lds, const Gemm g, const Sched& S, const Epi& E, int tid_in) {
;     ...
;             PG8_LDB(B0, 0, 0); PG8_LDB(B1, 0, 1); PG8_SCHED; PG8_LDA(At, 0, 0); PG8_STAGE(PG8_SA(1, 1), a1 + hstepA, voffA);
;             PG8_WAIT_V(8); PG8_WAIT_L(0); PG8_BAR; PG8_MMA(0, 0, At, B0); PG8_MMA(0, 1, At, B1); PG8_BAR; PG8_SCHED;
;             PG8_LDA(At, 0, 1); PG8_STAGE(PG8_SB(0, 0), b2, voffB); PG8_STAGE(PG8_SB(0, 1), b2 + hstepB, voffB); PG8_STAGE(PG8_SA(0, 0), a2, voffA);
;             PG8_WAIT_V(8); PG8_WAIT_L(0); PG8_BAR; PG8_MMA(1, 0, At, B0); PG8_MMA(1, 1, At, B1); PG8_BAR; PG8_SCHED;
.LBB0_1584:
	v_add_u32_e32 v133, 0x10000, v131
	ds_read_b128 v[134:137], v133
	ds_read_b128 v[138:141], v133 offset:1024
	ds_read_b128 v[142:145], v133 offset:2048
	ds_read_b128 v[146:149], v133 offset:3072
	v_add_u32_e32 v133, 0x14000, v131
	ds_read_b128 v[150:153], v133
	ds_read_b128 v[154:157], v133 offset:1024
	ds_read_b128 v[158:161], v133 offset:2048
	ds_read_b128 v[166:169], v133 offset:3072
	s_add_i32 s43, s38, s22
	s_add_i32 s42, s14, s22
	s_add_i32 s76, s12, s22
	s_addk_i32 s43, 0xff80
	s_sub_i32 s78, s43, 0x160000
	s_cmpk_eq_i32 s39, 0x54
	s_cselect_b32 s77, s16, s42
	s_mov_b32 m0, s68
	ds_read_b128 v[170:173], v132
	ds_read_b128 v[174:177], v132 offset:1024
	ds_read_b128 v[178:181], v132 offset:2048
	ds_read_b128 v[182:185], v132 offset:3072
	ds_read_b128 v[186:189], v132 offset:4096
	ds_read_b128 v[190:193], v132 offset:5120
	ds_read_b128 v[200:203], v132 offset:6144
	ds_read_b128 v[206:209], v132 offset:7168
	s_mov_b32 m0, s63
	s_nop 0
	buffer_load_dwordx4 v130, s[4:7], s78 offen lds
	s_mov_b32 m0, s68
	s_nop 0
	buffer_load_dwordx4 v0, s[4:7], s43 offen lds
	s_mov_b32 m0, s69
	s_nop 0
	buffer_load_dwordx4 v130, s[4:7], s43 offen lds
	s_waitcnt vmcnt(8)
	s_waitcnt lgkmcnt(0)
	s_barrier
	s_setprio 1
	v_mfma_f32_16x16x32_bf16 v[22:25], v[134:137], v[170:173], v[22:25]
	v_mfma_f32_16x16x32_bf16 v[14:17], v[142:145], v[170:173], v[14:17]
	v_mfma_f32_16x16x32_bf16 v[54:57], v[142:145], v[178:181], v[54:57]
	v_mfma_f32_16x16x32_bf16 v[74:77], v[134:137], v[178:181], v[74:77]
	v_mfma_f32_16x16x32_bf16 v[106:109], v[134:137], v[186:189], v[106:109]
	v_mfma_f32_16x16x32_bf16 v[102:105], v[142:145], v[186:189], v[102:105]
	v_mfma_f32_16x16x32_bf16 v[118:121], v[142:145], v[200:203], v[118:121]
	v_mfma_f32_16x16x32_bf16 v[122:125], v[134:137], v[200:203], v[122:125]
	v_mfma_f32_16x16x32_bf16 v[22:25], v[138:141], v[174:177], v[22:25]
	v_mfma_f32_16x16x32_bf16 v[14:17], v[146:149], v[174:177], v[14:17]
	v_mfma_f32_16x16x32_bf16 v[54:57], v[146:149], v[182:185], v[54:57]
	v_mfma_f32_16x16x32_bf16 v[74:77], v[138:141], v[182:185], v[74:77]
	v_mfma_f32_16x16x32_bf16 v[106:109], v[138:141], v[190:193], v[106:109]
	v_mfma_f32_16x16x32_bf16 v[102:105], v[146:149], v[190:193], v[102:105]
	v_mfma_f32_16x16x32_bf16 v[118:121], v[146:149], v[206:209], v[118:121]
	v_mfma_f32_16x16x32_bf16 v[122:125], v[138:141], v[206:209], v[122:125]
	v_mfma_f32_16x16x32_bf16 v[6:9], v[150:153], v[170:173], v[6:9]
	v_mfma_f32_16x16x32_bf16 v[18:21], v[158:161], v[170:173], v[18:21]
	v_mfma_f32_16x16x32_bf16 v[78:81], v[158:161], v[178:181], v[78:81]
	v_mfma_f32_16x16x32_bf16 v[50:53], v[150:153], v[178:181], v[50:53]
	v_mfma_f32_16x16x32_bf16 v[98:101], v[150:153], v[186:189], v[98:101]
	v_mfma_f32_16x16x32_bf16 v[110:113], v[158:161], v[186:189], v[110:113]
	v_mfma_f32_16x16x32_bf16 v[126:129], v[158:161], v[200:203], v[126:129]
	v_mfma_f32_16x16x32_bf16 v[114:117], v[150:153], v[200:203], v[114:117]
	v_mfma_f32_16x16x32_bf16 v[6:9], v[154:157], v[174:177], v[6:9]
	v_mfma_f32_16x16x32_bf16 v[18:21], v[166:169], v[174:177], v[18:21]
	v_mfma_f32_16x16x32_bf16 v[78:81], v[166:169], v[182:185], v[78:81]
	v_mfma_f32_16x16x32_bf16 v[50:53], v[154:157], v[182:185], v[50:53]
	v_mfma_f32_16x16x32_bf16 v[98:101], v[154:157], v[190:193], v[98:101]
	v_mfma_f32_16x16x32_bf16 v[110:113], v[166:169], v[190:193], v[110:113]
	v_mfma_f32_16x16x32_bf16 v[126:129], v[166:169], v[206:209], v[126:129]
	v_mfma_f32_16x16x32_bf16 v[114:117], v[154:157], v[206:209], v[114:117]
	s_setprio 0
	s_barrier
	s_cselect_b32 s76, s20, s76
	s_mov_b32 m0, s26
	s_mov_b32 s42, s6
	s_mov_b32 s43, s7
	s_sub_i32 s76, s76, s40
	ds_read_b128 v[170:173], v132 offset:16384
	ds_read_b128 v[174:177], v132 offset:17408
	ds_read_b128 v[178:181], v132 offset:18432
	ds_read_b128 v[182:185], v132 offset:19456
	ds_read_b128 v[186:189], v132 offset:20480
	ds_read_b128 v[190:193], v132 offset:21504
	ds_read_b128 v[200:203], v132 offset:22528
	ds_read_b128 v[206:209], v132 offset:23552
	buffer_load_dwordx4 v0, s[40:43], s76 offen lds
	s_mov_b32 m0, s44
	s_add_i32 s78, s76, 0x160000
	buffer_load_dwordx4 v130, s[40:43], s76 offen lds
	s_mov_b32 m0, s45
	s_sub_i32 s77, s77, s4
	buffer_load_dwordx4 v0, s[40:43], s78 offen lds
	s_mov_b32 m0, s46
	s_nop 0
	buffer_load_dwordx4 v130, s[40:43], s78 offen lds
	s_mov_b32 m0, s19
	s_nop 0
	buffer_load_dwordx4 v0, s[4:7], s77 offen lds
	s_waitcnt vmcnt(7)
	s_waitcnt lgkmcnt(0)
	s_barrier
	s_setprio 1
	v_mfma_f32_16x16x32_bf16 v[62:65], v[134:137], v[170:173], v[62:65]
	v_mfma_f32_16x16x32_bf16 v[46:49], v[142:145], v[170:173], v[46:49]
	v_mfma_f32_16x16x32_bf16 v[70:73], v[142:145], v[178:181], v[70:73]
	v_mfma_f32_16x16x32_bf16 v[82:85], v[134:137], v[178:181], v[82:85]
	v_mfma_f32_16x16x32_bf16 v[94:97], v[134:137], v[186:189], v[94:97]
	v_mfma_f32_16x16x32_bf16 v[90:93], v[142:145], v[186:189], v[90:93]
	v_mfma_f32_16x16x32_bf16 v[26:29], v[142:145], v[200:203], v[26:29]
	v_mfma_f32_16x16x32_bf16 v[38:41], v[134:137], v[200:203], v[38:41]
	v_mfma_f32_16x16x32_bf16 v[62:65], v[138:141], v[174:177], v[62:65]
	v_mfma_f32_16x16x32_bf16 v[46:49], v[146:149], v[174:177], v[46:49]
	v_mfma_f32_16x16x32_bf16 v[70:73], v[146:149], v[182:185], v[70:73]
	v_mfma_f32_16x16x32_bf16 v[82:85], v[138:141], v[182:185], v[82:85]
	v_mfma_f32_16x16x32_bf16 v[94:97], v[138:141], v[190:193], v[94:97]
	v_mfma_f32_16x16x32_bf16 v[90:93], v[146:149], v[190:193], v[90:93]
	v_mfma_f32_16x16x32_bf16 v[26:29], v[146:149], v[206:209], v[26:29]
	v_mfma_f32_16x16x32_bf16 v[38:41], v[138:141], v[206:209], v[38:41]
	v_mfma_f32_16x16x32_bf16 v[42:45], v[150:153], v[170:173], v[42:45]
	v_mfma_f32_16x16x32_bf16 v[30:33], v[158:161], v[170:173], v[30:33]
	v_mfma_f32_16x16x32_bf16 v[86:89], v[158:161], v[178:181], v[86:89]
	v_mfma_f32_16x16x32_bf16 v[66:69], v[150:153], v[178:181], v[66:69]
	v_mfma_f32_16x16x32_bf16 v[58:61], v[150:153], v[186:189], v[58:61]
	v_mfma_f32_16x16x32_bf16 v[34:37], v[158:161], v[186:189], v[34:37]
	v_mfma_f32_16x16x32_bf16 v[2:5], v[158:161], v[200:203], v[2:5]
	v_mfma_f32_16x16x32_bf16 v[10:13], v[150:153], v[200:203], v[10:13]
	v_mfma_f32_16x16x32_bf16 v[42:45], v[154:157], v[174:177], v[42:45]
	v_mfma_f32_16x16x32_bf16 v[30:33], v[166:169], v[174:177], v[30:33]
	v_mfma_f32_16x16x32_bf16 v[86:89], v[166:169], v[182:185], v[86:89]
	v_mfma_f32_16x16x32_bf16 v[66:69], v[154:157], v[182:185], v[66:69]
	v_mfma_f32_16x16x32_bf16 v[58:61], v[154:157], v[190:193], v[58:61]
	v_mfma_f32_16x16x32_bf16 v[34:37], v[166:169], v[190:193], v[34:37]
	v_mfma_f32_16x16x32_bf16 v[2:5], v[166:169], v[206:209], v[2:5]
	v_mfma_f32_16x16x32_bf16 v[10:13], v[154:157], v[206:209], v[10:13]
	s_setprio 0
	s_barrier
; #define PG8_STAGE(bufoff, gbase, voff) do { const int so_ = (int)(unsigned)((const char*)(gbase) - base_##voff); _Pragma("unroll") for (int _i = 0; _i < 2; ++_i) \
;         __builtin_amdgcn_raw_ptr_buffer_load_lds(rs_##voff, (PG8_LAS unsigned*)(lds + (bufoff) + ldsw + _i * 8192), 16, (int)(voff)[_i], so_, 0, 0); } while (0)
; #define PG8_LDA(dst, b, h) do { _Pragma("unroll") for (int m = 0; m < 4; ++m) _Pragma("unroll") for (int k = 0; k < 2; ++k) dst[m][k] = *(const PG8_LAS bf16x8*)(lds + PG8_SA(b, h) + aoff + m * 2048 + k * 1024); } while (0)
; #define PG8_LDB(dst, b, h) do { _Pragma("unroll") for (int n = 0; n < 2; ++n) _Pragma("unroll") for (int k = 0; k < 2; ++k) dst[n][k] = *(const PG8_LAS bf16x8*)(lds + PG8_SB(b, h) + boff + n * 2048 + k * 1024); } while (0)
; #define PG8_MMA(ai, bj, At, Bt) do { __builtin_amdgcn_s_setprio(1); _Pragma("unroll") for (int m = 0; m < 4; ++m) _Pragma("unroll") for (int n = 0; n < 2; ++n) _Pragma("unroll") for (int k = 0; k < 2; ++k) \
;         acc[ai][bj][m][n] = __builtin_amdgcn_mfma_f32_16x16x32_bf16(Bt[n][k], At[m][k], acc[ai][bj][m][n], 0, 0, 0); __builtin_amdgcn_s_setprio(0); } while (0)
; #define PG8_WAIT_V(n) asm volatile("s_waitcnt vmcnt(" #n ")" ::: "memory")
; #define PG8_WAIT_L(n) asm volatile("s_waitcnt lgkmcnt(" #n ")" ::: "memory")
; #define PG8_BAR __builtin_amdgcn_s_barrier()
; #define PG8_SCHED __builtin_amdgcn_sched_barrier(0)
; template <class Epi, class Sched, bool ALIGN_EPI = false, bool SP2 = false>
; __device__ __forceinline__ void gemm_phase(PG8_LAS unsigned char* lds, const Gemm g, const Sched& S, const Epi& E, int tid_in) {
;     ...
;             PG8_LDB(B0, 1, 0); PG8_LDB(B1, 1, 1); PG8_SCHED; PG8_LDA(At, 1, 0); PG8_STAGE(PG8_SA(0, 1), a2 + hstepA, voffA);
;             PG8_WAIT_V(8); PG8_WAIT_L(0); PG8_BAR; PG8_MMA(0, 0, At, B0); PG8_MMA(0, 1, At, B1); PG8_BAR; PG8_SCHED;
;             PG8_LDA(At, 1, 1); PG8_STAGE(PG8_SB(1, 0), b3, voffB); PG8_STAGE(PG8_SB(1, 1), b3 + hstepB, voffB); PG8_STAGE(PG8_SA(1, 0), a3, voffA);
	v_add_u32_e32 v133, 0x18000, v131
	ds_read_b128 v[134:137], v133
	ds_read_b128 v[138:141], v133 offset:1024
	ds_read_b128 v[142:145], v133 offset:2048
	ds_read_b128 v[146:149], v133 offset:3072
	v_add_u32_e32 v133, 0x1c000, v131
	ds_read_b128 v[150:153], v133
	ds_read_b128 v[154:157], v133 offset:1024
	ds_read_b128 v[158:161], v133 offset:2048
	ds_read_b128 v[166:169], v133 offset:3072
	s_add_i32 s78, s77, 0x160000
	s_mov_b32 m0, s48
	ds_read_b128 v[170:173], v132 offset:32768
	ds_read_b128 v[174:177], v132 offset:33792
	ds_read_b128 v[178:181], v132 offset:34816
	ds_read_b128 v[182:185], v132 offset:35840
	ds_read_b128 v[186:189], v132 offset:36864
	ds_read_b128 v[190:193], v132 offset:37888
	ds_read_b128 v[200:203], v132 offset:38912
	ds_read_b128 v[206:209], v132 offset:39936
	s_mov_b32 m0, s47
	s_nop 0
	buffer_load_dwordx4 v130, s[4:7], s77 offen lds
	s_mov_b32 m0, s48
	s_nop 0
	buffer_load_dwordx4 v0, s[4:7], s78 offen lds
	s_mov_b32 m0, s49
	s_nop 0
	buffer_load_dwordx4 v130, s[4:7], s78 offen lds
	s_waitcnt vmcnt(8)
	s_waitcnt lgkmcnt(0)
	s_barrier
	s_setprio 1
	v_mfma_f32_16x16x32_bf16 v[22:25], v[134:137], v[170:173], v[22:25]
	v_mfma_f32_16x16x32_bf16 v[14:17], v[142:145], v[170:173], v[14:17]
	v_mfma_f32_16x16x32_bf16 v[54:57], v[142:145], v[178:181], v[54:57]
	v_mfma_f32_16x16x32_bf16 v[74:77], v[134:137], v[178:181], v[74:77]
	v_mfma_f32_16x16x32_bf16 v[106:109], v[134:137], v[186:189], v[106:109]
	v_mfma_f32_16x16x32_bf16 v[102:105], v[142:145], v[186:189], v[102:105]
	v_mfma_f32_16x16x32_bf16 v[118:121], v[142:145], v[200:203], v[118:121]
	v_mfma_f32_16x16x32_bf16 v[122:125], v[134:137], v[200:203], v[122:125]
	v_mfma_f32_16x16x32_bf16 v[22:25], v[138:141], v[174:177], v[22:25]
	v_mfma_f32_16x16x32_bf16 v[14:17], v[146:149], v[174:177], v[14:17]
	v_mfma_f32_16x16x32_bf16 v[54:57], v[146:149], v[182:185], v[54:57]
	v_mfma_f32_16x16x32_bf16 v[74:77], v[138:141], v[182:185], v[74:77]
	v_mfma_f32_16x16x32_bf16 v[106:109], v[138:141], v[190:193], v[106:109]
	v_mfma_f32_16x16x32_bf16 v[102:105], v[146:149], v[190:193], v[102:105]
	v_mfma_f32_16x16x32_bf16 v[118:121], v[146:149], v[206:209], v[118:121]
	v_mfma_f32_16x16x32_bf16 v[122:125], v[138:141], v[206:209], v[122:125]
	v_mfma_f32_16x16x32_bf16 v[6:9], v[150:153], v[170:173], v[6:9]
	v_mfma_f32_16x16x32_bf16 v[18:21], v[158:161], v[170:173], v[18:21]
	v_mfma_f32_16x16x32_bf16 v[78:81], v[158:161], v[178:181], v[78:81]
	v_mfma_f32_16x16x32_bf16 v[50:53], v[150:153], v[178:181], v[50:53]
	v_mfma_f32_16x16x32_bf16 v[98:101], v[150:153], v[186:189], v[98:101]
	v_mfma_f32_16x16x32_bf16 v[110:113], v[158:161], v[186:189], v[110:113]
	v_mfma_f32_16x16x32_bf16 v[126:129], v[158:161], v[200:203], v[126:129]
	v_mfma_f32_16x16x32_bf16 v[114:117], v[150:153], v[200:203], v[114:117]
	v_mfma_f32_16x16x32_bf16 v[6:9], v[154:157], v[174:177], v[6:9]
	v_mfma_f32_16x16x32_bf16 v[18:21], v[166:169], v[174:177], v[18:21]
	v_mfma_f32_16x16x32_bf16 v[78:81], v[166:169], v[182:185], v[78:81]
	v_mfma_f32_16x16x32_bf16 v[50:53], v[154:157], v[182:185], v[50:53]
	v_mfma_f32_16x16x32_bf16 v[98:101], v[154:157], v[190:193], v[98:101]
	v_mfma_f32_16x16x32_bf16 v[110:113], v[166:169], v[190:193], v[110:113]
	v_mfma_f32_16x16x32_bf16 v[126:129], v[166:169], v[206:209], v[126:129]
	v_mfma_f32_16x16x32_bf16 v[114:117], v[154:157], v[206:209], v[114:117]
	s_setprio 0
	s_barrier
	s_mov_b32 m0, s60
	s_add_i32 s78, s76, 0x80
	ds_read_b128 v[170:173], v132 offset:49152
	ds_read_b128 v[174:177], v132 offset:50176
	ds_read_b128 v[178:181], v132 offset:51200
	ds_read_b128 v[182:185], v132 offset:52224
	ds_read_b128 v[186:189], v132 offset:53248
	ds_read_b128 v[190:193], v132 offset:54272
	ds_read_b128 v[200:203], v132 offset:55296
	ds_read_b128 v[206:209], v132 offset:56320
	buffer_load_dwordx4 v0, s[40:43], s78 offen lds
	s_mov_b32 m0, s61
	s_add_i32 s76, s76, 0x160080
	buffer_load_dwordx4 v130, s[40:43], s78 offen lds
	s_mov_b32 m0, s66
	s_addk_i32 s77, 0x80
	buffer_load_dwordx4 v0, s[40:43], s76 offen lds
	s_mov_b32 m0, s67
	s_nop 0
	buffer_load_dwordx4 v130, s[40:43], s76 offen lds
	s_mov_b32 m0, s62
	s_nop 0
	buffer_load_dwordx4 v0, s[4:7], s77 offen lds
	s_waitcnt vmcnt(7)
	s_waitcnt lgkmcnt(0)
	s_barrier
; #define PG8_MMA(ai, bj, At, Bt) do { __builtin_amdgcn_s_setprio(1); _Pragma("unroll") for (int m = 0; m < 4; ++m) _Pragma("unroll") for (int n = 0; n < 2; ++n) _Pragma("unroll") for (int k = 0; k < 2; ++k) \
;         acc[ai][bj][m][n] = __builtin_amdgcn_mfma_f32_16x16x32_bf16(Bt[n][k], At[m][k], acc[ai][bj][m][n], 0, 0, 0); __builtin_amdgcn_s_setprio(0); } while (0)
; #define PG8_WAIT_V(n) asm volatile("s_waitcnt vmcnt(" #n ")" ::: "memory")
; #define PG8_WAIT_L(n) asm volatile("s_waitcnt lgkmcnt(" #n ")" ::: "memory")
; #define PG8_BAR __builtin_amdgcn_s_barrier()
; #define PG8_SCHED __builtin_amdgcn_sched_barrier(0)
; template <class Epi, class Sched, bool ALIGN_EPI = false, bool SP2 = false>
; __device__ __forceinline__ void gemm_phase(PG8_LAS unsigned char* lds, const Gemm g, const Sched& S, const Epi& E, int tid_in) {
;     ...
;             PG8_WAIT_V(8); PG8_WAIT_L(0); PG8_BAR; PG8_MMA(1, 0, At, B0); PG8_MMA(1, 1, At, B1); PG8_BAR; PG8_SCHED;
;     ...
;         if (zero_acc) {
; #pragma unroll
;         for (int a = 0; a < 2; ++a)
; #pragma unroll
;             for (int b = 0; b < 2; ++b)
; #pragma unroll
;                 for (int m = 0; m < 4; ++m)
; #pragma unroll
;                     for (int n = 0; n < 2; ++n) acc[a][b][m][n] = (f32x4){0.f, 0.f, 0.f, 0.f};
;         }
;         cur = nxt; cA = nA; cB = nB; ++ui;
	s_setprio 1
	v_mfma_f32_16x16x32_bf16 v[62:65], v[134:137], v[170:173], v[62:65]
	v_mfma_f32_16x16x32_bf16 v[46:49], v[142:145], v[170:173], v[46:49]
	v_mfma_f32_16x16x32_bf16 v[70:73], v[142:145], v[178:181], v[70:73]
	v_mfma_f32_16x16x32_bf16 v[82:85], v[134:137], v[178:181], v[82:85]
	v_mfma_f32_16x16x32_bf16 v[94:97], v[134:137], v[186:189], v[94:97]
	v_mfma_f32_16x16x32_bf16 v[90:93], v[142:145], v[186:189], v[90:93]
	v_mfma_f32_16x16x32_bf16 v[26:29], v[142:145], v[200:203], v[26:29]
	v_mfma_f32_16x16x32_bf16 v[38:41], v[134:137], v[200:203], v[38:41]
	v_mfma_f32_16x16x32_bf16 v[62:65], v[138:141], v[174:177], v[62:65]
	v_mfma_f32_16x16x32_bf16 v[46:49], v[146:149], v[174:177], v[46:49]
	v_mfma_f32_16x16x32_bf16 v[70:73], v[146:149], v[182:185], v[70:73]
	v_mfma_f32_16x16x32_bf16 v[82:85], v[138:141], v[182:185], v[82:85]
	v_mfma_f32_16x16x32_bf16 v[94:97], v[138:141], v[190:193], v[94:97]
	v_mfma_f32_16x16x32_bf16 v[90:93], v[146:149], v[190:193], v[90:93]
	v_mfma_f32_16x16x32_bf16 v[26:29], v[146:149], v[206:209], v[26:29]
	v_mfma_f32_16x16x32_bf16 v[38:41], v[138:141], v[206:209], v[38:41]
	v_mfma_f32_16x16x32_bf16 v[42:45], v[150:153], v[170:173], v[42:45]
	v_mfma_f32_16x16x32_bf16 v[30:33], v[158:161], v[170:173], v[30:33]
	v_mfma_f32_16x16x32_bf16 v[86:89], v[158:161], v[178:181], v[86:89]
	v_mfma_f32_16x16x32_bf16 v[66:69], v[150:153], v[178:181], v[66:69]
	v_mfma_f32_16x16x32_bf16 v[58:61], v[150:153], v[186:189], v[58:61]
	v_mfma_f32_16x16x32_bf16 v[34:37], v[158:161], v[186:189], v[34:37]
	v_mfma_f32_16x16x32_bf16 v[2:5], v[158:161], v[200:203], v[2:5]
	v_mfma_f32_16x16x32_bf16 v[10:13], v[150:153], v[200:203], v[10:13]
	v_mfma_f32_16x16x32_bf16 v[42:45], v[154:157], v[174:177], v[42:45]
	v_mfma_f32_16x16x32_bf16 v[30:33], v[166:169], v[174:177], v[30:33]
	v_mfma_f32_16x16x32_bf16 v[86:89], v[166:169], v[182:185], v[86:89]
	v_mfma_f32_16x16x32_bf16 v[66:69], v[154:157], v[182:185], v[66:69]
	v_mfma_f32_16x16x32_bf16 v[58:61], v[154:157], v[190:193], v[58:61]
	v_mfma_f32_16x16x32_bf16 v[34:37], v[166:169], v[190:193], v[34:37]
	v_mfma_f32_16x16x32_bf16 v[2:5], v[166:169], v[206:209], v[2:5]
	v_mfma_f32_16x16x32_bf16 v[10:13], v[154:157], v[206:209], v[10:13]
	s_setprio 0
	s_barrier
	s_add_i32 s39, s39, 2
	s_add_u32 s22, s22, 0x100
	s_addc_u32 s23, s23, 0
	s_cmpk_gt_u32 s39, 0x55
	s_cbranch_scc0 .LBB0_1584
	s_and_b64 vcc, exec, s[36:37]
	s_cbranch_vccnz .LBB0_1572
	v_mov_b32_e32 v2, 0
	s_mov_b32 s10, s73
	s_mov_b32 s25, s74
	s_mov_b64 s[12:13], s[20:21]
	s_mov_b64 s[14:15], s[16:17]
	s_mov_b32 s72, s75
	v_mov_b32_e32 v3, v2
	v_mov_b32_e32 v4, v2
	v_mov_b32_e32 v5, v2
	v_mov_b32_e32 v10, v2
	v_mov_b32_e32 v11, v2
	v_mov_b32_e32 v12, v2
	v_mov_b32_e32 v13, v2
	v_mov_b32_e32 v34, v2
	v_mov_b32_e32 v35, v2
	v_mov_b32_e32 v36, v2
	v_mov_b32_e32 v37, v2
	v_mov_b32_e32 v58, v2
	v_mov_b32_e32 v59, v2
	v_mov_b32_e32 v60, v2
	v_mov_b32_e32 v61, v2
	v_mov_b32_e32 v86, v2
	v_mov_b32_e32 v87, v2
	v_mov_b32_e32 v88, v2
	v_mov_b32_e32 v89, v2
	v_mov_b32_e32 v66, v2
	v_mov_b32_e32 v67, v2
	v_mov_b32_e32 v68, v2
	v_mov_b32_e32 v69, v2
	v_mov_b32_e32 v30, v2
	v_mov_b32_e32 v31, v2
	v_mov_b32_e32 v32, v2
	v_mov_b32_e32 v33, v2
	v_mov_b32_e32 v42, v2
	v_mov_b32_e32 v43, v2
	v_mov_b32_e32 v44, v2
	v_mov_b32_e32 v45, v2
	v_mov_b32_e32 v26, v2
	v_mov_b32_e32 v27, v2
	v_mov_b32_e32 v28, v2
	v_mov_b32_e32 v29, v2
	v_mov_b32_e32 v38, v2
	v_mov_b32_e32 v39, v2
	v_mov_b32_e32 v40, v2
	v_mov_b32_e32 v41, v2
	v_mov_b32_e32 v90, v2
	v_mov_b32_e32 v91, v2
	v_mov_b32_e32 v92, v2
	v_mov_b32_e32 v93, v2
	v_mov_b32_e32 v94, v2
	v_mov_b32_e32 v95, v2
	v_mov_b32_e32 v96, v2
	v_mov_b32_e32 v97, v2
	v_mov_b32_e32 v70, v2
	v_mov_b32_e32 v71, v2
	v_mov_b32_e32 v72, v2
	v_mov_b32_e32 v73, v2
	v_mov_b32_e32 v82, v2
	v_mov_b32_e32 v83, v2
	v_mov_b32_e32 v84, v2
	v_mov_b32_e32 v85, v2
	v_mov_b32_e32 v46, v2
	v_mov_b32_e32 v47, v2
	v_mov_b32_e32 v48, v2
	v_mov_b32_e32 v49, v2
	v_mov_b32_e32 v62, v2
	v_mov_b32_e32 v63, v2
	v_mov_b32_e32 v64, v2
	v_mov_b32_e32 v65, v2
	v_mov_b32_e32 v126, v2
	v_mov_b32_e32 v127, v2
	v_mov_b32_e32 v128, v2
	v_mov_b32_e32 v129, v2
	v_mov_b32_e32 v114, v2
	v_mov_b32_e32 v115, v2
	v_mov_b32_e32 v116, v2
	v_mov_b32_e32 v117, v2
	v_mov_b32_e32 v110, v2
	v_mov_b32_e32 v111, v2
	v_mov_b32_e32 v112, v2
	v_mov_b32_e32 v113, v2
	v_mov_b32_e32 v98, v2
	v_mov_b32_e32 v99, v2
	v_mov_b32_e32 v100, v2
	v_mov_b32_e32 v101, v2
	v_mov_b32_e32 v78, v2
	v_mov_b32_e32 v79, v2
	v_mov_b32_e32 v80, v2
	v_mov_b32_e32 v81, v2
	v_mov_b32_e32 v50, v2
	v_mov_b32_e32 v51, v2
	v_mov_b32_e32 v52, v2
	v_mov_b32_e32 v53, v2
	v_mov_b32_e32 v18, v2
	v_mov_b32_e32 v19, v2
	v_mov_b32_e32 v20, v2
	v_mov_b32_e32 v21, v2
	v_mov_b32_e32 v6, v2
	v_mov_b32_e32 v7, v2
	v_mov_b32_e32 v8, v2
	v_mov_b32_e32 v9, v2
	v_mov_b32_e32 v118, v2
	v_mov_b32_e32 v119, v2
	v_mov_b32_e32 v120, v2
	v_mov_b32_e32 v121, v2
	v_mov_b32_e32 v122, v2
	v_mov_b32_e32 v123, v2
	v_mov_b32_e32 v124, v2
	v_mov_b32_e32 v125, v2
	v_mov_b32_e32 v102, v2
	v_mov_b32_e32 v103, v2
	v_mov_b32_e32 v104, v2
	v_mov_b32_e32 v105, v2
	v_mov_b32_e32 v106, v2
	v_mov_b32_e32 v107, v2
	v_mov_b32_e32 v108, v2
	v_mov_b32_e32 v109, v2
	v_mov_b32_e32 v54, v2
	v_mov_b32_e32 v55, v2
	v_mov_b32_e32 v56, v2
	v_mov_b32_e32 v57, v2
	v_mov_b32_e32 v74, v2
	v_mov_b32_e32 v75, v2
	v_mov_b32_e32 v76, v2
	v_mov_b32_e32 v77, v2
	v_mov_b32_e32 v14, v2
	v_mov_b32_e32 v15, v2
	v_mov_b32_e32 v16, v2
	v_mov_b32_e32 v17, v2
	v_mov_b32_e32 v22, v2
	v_mov_b32_e32 v23, v2
	v_mov_b32_e32 v24, v2
	v_mov_b32_e32 v25, v2
	s_branch .LBB0_1572
